# v76 + row-group sum shuffles in the four residual/final epilogues via v_permlane16/32_swap instead of ds_bpermute
# baseline (speedup 1.0000x reference)
.LBB0_592:
	s_waitcnt vmcnt(15)
	s_nop 0
	v_mov_b32_e32 v158, v172
	v_mov_b32_e32 v159, v173
	v_mov_b32_e32 v160, v174
	v_mov_b32_e32 v161, v175
	s_waitcnt vmcnt(14)
	s_nop 0
	v_mov_b32_e32 v162, v176
	v_mov_b32_e32 v163, v177
	v_mov_b32_e32 v164, v178
	v_mov_b32_e32 v165, v179
	v_lshl_add_u64 v[168:169], v[144:145], 1, s[14:15]
	v_xor_b32_e32 v157, 32, v156
	v_pk_add_f32 v[126:127], v[126:127], v[160:161]
	v_pk_add_f32 v[170:171], v[124:125], v[158:159]
	v_pk_add_f32 v[164:165], v[122:123], v[164:165]
	v_pk_add_f32 v[162:163], v[120:121], v[162:163]
	v_cvt_pk_bf16_f32 v120, v170, v171
	v_cvt_pk_bf16_f32 v121, v126, v127
	v_mul_f32_e32 v127, v127, v127
	v_cvt_pk_bf16_f32 v122, v162, v163
	v_cvt_pk_bf16_f32 v123, v164, v165
	global_store_dwordx4 v[168:169], v[120:123], off
	s_waitcnt vmcnt(13)
	s_nop 0
	v_mov_b32_e32 v122, v180
	v_mov_b32_e32 v123, v181
	v_mov_b32_e32 v124, v182
	v_mov_b32_e32 v125, v183
	s_nop 0
	s_waitcnt vmcnt(12)
	s_nop 0
	v_mov_b32_e32 v158, v184
	v_mov_b32_e32 v159, v185
	v_mov_b32_e32 v160, v186
	v_mov_b32_e32 v161, v187
	v_mul_f32_e32 v166, v171, v171
	v_mul_f32_e32 v163, v163, v163
	v_fmac_f32_e32 v166, v170, v170
	v_fmac_f32_e32 v127, v126, v126
	v_mul_f32_e32 v165, v165, v165
	v_fmac_f32_e32 v163, v162, v162
	v_add_f32_e32 v126, v166, v127
	v_fmac_f32_e32 v165, v164, v164
	v_add_f32_e32 v126, v126, v163
	v_add_f32_e32 v162, v165, v126
	v_and_b32_e32 v121, 64, v156
	v_xor_b32_e32 v120, 16, v156
	v_add_u32_e32 v121, 64, v121
	v_cmp_lt_i32_e32 vcc, v120, v121
	v_pk_add_f32 v[118:119], v[118:119], v[124:125]
	v_pk_add_f32 v[116:117], v[116:117], v[122:123]
	v_pk_add_f32 v[126:127], v[114:115], v[160:161]
	v_pk_add_f32 v[112:113], v[112:113], v[158:159]
	v_mul_f32_e32 v114, v117, v117
	v_mul_f32_e32 v115, v119, v119
	v_mul_f32_e32 v122, v113, v113
	v_fmac_f32_e32 v114, v116, v116
	v_fmac_f32_e32 v115, v118, v118
	v_mul_f32_e32 v123, v127, v127
	v_fmac_f32_e32 v122, v112, v112
	v_add_f32_e32 v114, v114, v115
	v_fmac_f32_e32 v123, v126, v126
	v_add_f32_e32 v114, v114, v122
	v_cndmask_b32_e32 v120, v156, v120, vcc
	v_add_f32_e32 v114, v123, v114
	v_lshlrev_b32_e32 v120, 2, v120
	v_add_f32_e32 v114, v162, v114
	v_mov_b32_e32 v251, v114
	s_nop 1
	v_permlane16_swap_b32_e32 v251, v115
	s_nop 1
	v_permlane16_swap_b32_e32 v115, v251
	v_cmp_lt_i32_e32 vcc, v157, v121
	v_cvt_pk_bf16_f32 v122, v116, v117
	v_cvt_pk_bf16_f32 v123, v118, v119
	v_cvt_pk_bf16_f32 v124, v112, v113
	s_waitcnt lgkmcnt(0)
	v_add_f32_e32 v115, v114, v115
	v_lshl_add_u64 v[112:113], v[148:149], 2, s[16:17]
	v_cndmask_b32_e32 v121, v156, v157, vcc
	v_lshlrev_b32_e32 v114, 2, v121
	v_mov_b32_e32 v251, v115
	s_nop 1
	v_permlane32_swap_b32_e32 v251, v116
	s_nop 1
	v_permlane32_swap_b32_e32 v116, v251
	v_cvt_pk_bf16_f32 v125, v126, v127
	global_store_dwordx4 v[168:169], v[122:125], off offset:256
	s_and_saveexec_b64 s[40:41], s[6:7]
	s_cbranch_execz .LBB0_594
	s_waitcnt lgkmcnt(0)
	v_add_f32_e32 v115, v115, v116
	global_atomic_add_f32 v[112:113], v115, off
.LBB0_594:
	s_or_b64 exec, exec, s[40:41]
	s_waitcnt lgkmcnt(0)
	v_or_b32_e32 v116, 16, v148
	v_ashrrev_i32_e32 v117, 31, v116
	v_lshlrev_b64 v[116:117], 11, v[116:117]
	v_lshl_add_u64 v[126:127], v[116:117], 0, v[146:147]
	v_lshl_add_u64 v[158:159], v[126:127], 2, s[10:11]
	s_waitcnt vmcnt(11)
	s_nop 0
	v_mov_b32_e32 v116, v188
	v_mov_b32_e32 v117, v189
	v_mov_b32_e32 v118, v190
	v_mov_b32_e32 v119, v191
	s_waitcnt vmcnt(10)
	s_nop 0
	v_mov_b32_e32 v122, v196
	v_mov_b32_e32 v123, v197
	v_mov_b32_e32 v124, v198
	v_mov_b32_e32 v125, v199
	v_lshl_add_u64 v[126:127], v[126:127], 1, s[14:15]
	v_pk_add_f32 v[118:119], v[110:111], v[118:119]
	v_pk_add_f32 v[116:117], v[108:109], v[116:117]
	v_pk_add_f32 v[124:125], v[106:107], v[124:125]
	v_pk_add_f32 v[122:123], v[104:105], v[122:123]
	v_cvt_pk_bf16_f32 v104, v116, v117
	v_cvt_pk_bf16_f32 v105, v118, v119
	v_mul_f32_e32 v115, v117, v117
	v_cvt_pk_bf16_f32 v106, v122, v123
	v_cvt_pk_bf16_f32 v107, v124, v125
	global_store_dwordx4 v[126:127], v[104:107], off
	s_waitcnt vmcnt(9)
	s_nop 0
	v_mov_b32_e32 v104, v200
	v_mov_b32_e32 v105, v201
	v_mov_b32_e32 v106, v202
	v_mov_b32_e32 v107, v203
	s_nop 0
	s_waitcnt vmcnt(8)
	s_nop 0
	v_mov_b32_e32 v108, v204
	v_mov_b32_e32 v109, v205
	v_mov_b32_e32 v110, v206
	v_mov_b32_e32 v111, v207
	v_mul_f32_e32 v117, v119, v119
	v_mul_f32_e32 v119, v123, v123
	v_fmac_f32_e32 v115, v116, v116
	v_fmac_f32_e32 v117, v118, v118
	v_mul_f32_e32 v121, v125, v125
	v_fmac_f32_e32 v119, v122, v122
	v_add_f32_e32 v115, v115, v117
	v_fmac_f32_e32 v121, v124, v124
	v_add_f32_e32 v115, v115, v119
	v_add_f32_e32 v115, v121, v115
	v_pk_add_f32 v[102:103], v[102:103], v[106:107]
	v_pk_add_f32 v[100:101], v[100:101], v[104:105]
	v_pk_add_f32 v[106:107], v[96:97], v[108:109]
	v_mul_f32_e32 v96, v101, v101
	v_mul_f32_e32 v97, v103, v103
	v_pk_add_f32 v[104:105], v[98:99], v[110:111]
	v_mul_f32_e32 v98, v107, v107
	v_fmac_f32_e32 v96, v100, v100
	v_fmac_f32_e32 v97, v102, v102
	v_mul_f32_e32 v99, v105, v105
	v_fmac_f32_e32 v98, v106, v106
	v_add_f32_e32 v96, v96, v97
	v_add_f32_e32 v96, v96, v98
	v_fmac_f32_e32 v99, v104, v104
	v_add_f32_e32 v96, v99, v96
	v_add_f32_e32 v96, v115, v96
	v_mov_b32_e32 v251, v96
	s_nop 1
	v_permlane16_swap_b32_e32 v251, v97
	s_nop 1
	v_permlane16_swap_b32_e32 v97, v251
	v_cvt_pk_bf16_f32 v98, v100, v101
	v_cvt_pk_bf16_f32 v99, v102, v103
	v_cvt_pk_bf16_f32 v100, v106, v107
	v_cvt_pk_bf16_f32 v101, v104, v105
	s_waitcnt lgkmcnt(0)
	v_add_f32_e32 v96, v96, v97
	v_mov_b32_e32 v251, v96
	s_nop 1
	v_permlane32_swap_b32_e32 v251, v97
	s_nop 1
	v_permlane32_swap_b32_e32 v97, v251
	global_store_dwordx4 v[126:127], v[98:101], off offset:256
	s_and_saveexec_b64 s[40:41], s[6:7]
	s_cbranch_execz .LBB0_596
	s_waitcnt lgkmcnt(0)
	v_add_f32_e32 v96, v96, v97
	global_atomic_add_f32 v[112:113], v96, off offset:64
.LBB0_596:
	s_or_b64 exec, exec, s[40:41]
	v_add_co_u32_e32 v242, vcc, 0x100000, v244
	s_nop 1
	v_addc_co_u32_e32 v243, vcc, 0, v245, vcc
	global_load_dwordx4 v[172:175], v[242:243], off nt
	global_load_dwordx4 v[176:179], v[242:243], off offset:16 nt
	global_load_dwordx4 v[180:183], v[242:243], off offset:512 nt
	global_load_dwordx4 v[184:187], v[242:243], off offset:528 nt
	v_add_co_u32_e32 v240, vcc, 0x120000, v244
	s_nop 1
	v_addc_co_u32_e32 v241, vcc, 0, v245, vcc
	global_load_dwordx4 v[188:191], v[240:241], off nt
	global_load_dwordx4 v[196:199], v[240:241], off offset:16 nt
	global_load_dwordx4 v[200:203], v[240:241], off offset:512 nt
	global_load_dwordx4 v[204:207], v[240:241], off offset:528 nt
	v_or_b32_e32 v96, 32, v148
	s_waitcnt lgkmcnt(0)
	v_ashrrev_i32_e32 v97, 31, v96
	v_lshlrev_b64 v[96:97], 11, v[96:97]
	v_lshl_add_u64 v[104:105], v[96:97], 0, v[146:147]
	v_lshl_add_u64 v[106:107], v[104:105], 2, s[10:11]
	s_waitcnt vmcnt(15)
	s_nop 0
	v_mov_b32_e32 v96, v208
	v_mov_b32_e32 v97, v209
	v_mov_b32_e32 v98, v210
	v_mov_b32_e32 v99, v211
	s_waitcnt vmcnt(14)
	s_nop 0
	v_mov_b32_e32 v100, v212
	v_mov_b32_e32 v101, v213
	v_mov_b32_e32 v102, v214
	v_mov_b32_e32 v103, v215
	v_lshl_add_u64 v[104:105], v[104:105], 1, s[14:15]
	v_pk_add_f32 v[98:99], v[94:95], v[98:99]
	v_pk_add_f32 v[96:97], v[92:93], v[96:97]
	v_pk_add_f32 v[102:103], v[90:91], v[102:103]
	v_pk_add_f32 v[100:101], v[88:89], v[100:101]
	v_cvt_pk_bf16_f32 v88, v96, v97
	v_cvt_pk_bf16_f32 v89, v98, v99
	v_mul_f32_e32 v97, v97, v97
	v_cvt_pk_bf16_f32 v90, v100, v101
	v_cvt_pk_bf16_f32 v91, v102, v103
	global_store_dwordx4 v[104:105], v[88:91], off
	s_waitcnt vmcnt(13)
	s_nop 0
	v_mov_b32_e32 v88, v216
	v_mov_b32_e32 v89, v217
	v_mov_b32_e32 v90, v218
	v_mov_b32_e32 v91, v219
	s_nop 0
	s_waitcnt vmcnt(12)
	s_nop 0
	v_mov_b32_e32 v92, v220
	v_mov_b32_e32 v93, v221
	v_mov_b32_e32 v94, v222
	v_mov_b32_e32 v95, v223
	v_mul_f32_e32 v99, v99, v99
	v_mul_f32_e32 v101, v101, v101
	v_fmac_f32_e32 v97, v96, v96
	v_fmac_f32_e32 v99, v98, v98
	v_mul_f32_e32 v103, v103, v103
	v_fmac_f32_e32 v101, v100, v100
	v_add_f32_e32 v96, v97, v99
	v_fmac_f32_e32 v103, v102, v102
	v_add_f32_e32 v96, v96, v101
	v_add_f32_e32 v96, v103, v96
	v_pk_add_f32 v[86:87], v[86:87], v[90:91]
	v_pk_add_f32 v[84:85], v[84:85], v[88:89]
	v_pk_add_f32 v[90:91], v[80:81], v[92:93]
	v_mul_f32_e32 v80, v85, v85
	v_mul_f32_e32 v81, v87, v87
	v_pk_add_f32 v[88:89], v[82:83], v[94:95]
	v_mul_f32_e32 v82, v91, v91
	v_fmac_f32_e32 v80, v84, v84
	v_fmac_f32_e32 v81, v86, v86
	v_mul_f32_e32 v83, v89, v89
	v_fmac_f32_e32 v82, v90, v90
	v_add_f32_e32 v80, v80, v81
	v_add_f32_e32 v80, v80, v82
	v_fmac_f32_e32 v83, v88, v88
	v_add_f32_e32 v80, v83, v80
	v_add_f32_e32 v80, v96, v80
	v_mov_b32_e32 v251, v80
	s_nop 1
	v_permlane16_swap_b32_e32 v251, v81
	s_nop 1
	v_permlane16_swap_b32_e32 v81, v251
	v_cvt_pk_bf16_f32 v82, v84, v85
	v_cvt_pk_bf16_f32 v83, v86, v87
	v_cvt_pk_bf16_f32 v84, v90, v91
	v_cvt_pk_bf16_f32 v85, v88, v89
	s_waitcnt lgkmcnt(0)
	v_add_f32_e32 v80, v80, v81
	v_mov_b32_e32 v251, v80
	s_nop 1
	v_permlane32_swap_b32_e32 v251, v81
	s_nop 1
	v_permlane32_swap_b32_e32 v81, v251
	global_store_dwordx4 v[104:105], v[82:85], off offset:256
	s_and_saveexec_b64 s[40:41], s[6:7]
	s_cbranch_execz .LBB0_598
	s_waitcnt lgkmcnt(0)
	v_add_f32_e32 v80, v80, v81
	global_atomic_add_f32 v[112:113], v80, off offset:128
.LBB0_598:
	s_or_b64 exec, exec, s[40:41]
	v_or_b32_e32 v80, 48, v148
	s_waitcnt lgkmcnt(0)
	v_ashrrev_i32_e32 v81, 31, v80
	v_lshlrev_b64 v[80:81], 11, v[80:81]
	v_lshl_add_u64 v[88:89], v[80:81], 0, v[146:147]
	v_lshl_add_u64 v[90:91], v[88:89], 2, s[10:11]
	s_waitcnt vmcnt(11)
	s_nop 0
	v_mov_b32_e32 v80, v224
	v_mov_b32_e32 v81, v225
	v_mov_b32_e32 v82, v226
	v_mov_b32_e32 v83, v227
	s_waitcnt vmcnt(10)
	s_nop 0
	v_mov_b32_e32 v84, v228
	v_mov_b32_e32 v85, v229
	v_mov_b32_e32 v86, v230
	v_mov_b32_e32 v87, v231
	v_lshl_add_u64 v[88:89], v[88:89], 1, s[14:15]
	v_pk_add_f32 v[82:83], v[78:79], v[82:83]
	v_pk_add_f32 v[80:81], v[76:77], v[80:81]
	v_pk_add_f32 v[86:87], v[74:75], v[86:87]
	v_pk_add_f32 v[84:85], v[72:73], v[84:85]
	v_cvt_pk_bf16_f32 v72, v80, v81
	v_cvt_pk_bf16_f32 v73, v82, v83
	v_mul_f32_e32 v81, v81, v81
	v_cvt_pk_bf16_f32 v74, v84, v85
	v_cvt_pk_bf16_f32 v75, v86, v87
	global_store_dwordx4 v[88:89], v[72:75], off
	s_waitcnt vmcnt(9)
	s_nop 0
	v_mov_b32_e32 v72, v232
	v_mov_b32_e32 v73, v233
	v_mov_b32_e32 v74, v234
	v_mov_b32_e32 v75, v235
	s_nop 0
	s_waitcnt vmcnt(8)
	s_nop 0
	v_mov_b32_e32 v76, v236
	v_mov_b32_e32 v77, v237
	v_mov_b32_e32 v78, v238
	v_mov_b32_e32 v79, v239
	v_mul_f32_e32 v83, v83, v83
	v_mul_f32_e32 v85, v85, v85
	v_fmac_f32_e32 v81, v80, v80
	v_fmac_f32_e32 v83, v82, v82
	v_mul_f32_e32 v87, v87, v87
	v_fmac_f32_e32 v85, v84, v84
	v_add_f32_e32 v80, v81, v83
	v_fmac_f32_e32 v87, v86, v86
	v_add_f32_e32 v80, v80, v85
	v_add_f32_e32 v80, v87, v80
	v_pk_add_f32 v[70:71], v[70:71], v[74:75]
	v_pk_add_f32 v[68:69], v[68:69], v[72:73]
	v_pk_add_f32 v[74:75], v[64:65], v[76:77]
	v_mul_f32_e32 v64, v69, v69
	v_mul_f32_e32 v65, v71, v71
	v_pk_add_f32 v[72:73], v[66:67], v[78:79]
	v_mul_f32_e32 v66, v75, v75
	v_fmac_f32_e32 v64, v68, v68
	v_fmac_f32_e32 v65, v70, v70
	v_mul_f32_e32 v67, v73, v73
	v_fmac_f32_e32 v66, v74, v74
	v_add_f32_e32 v64, v64, v65
	v_add_f32_e32 v64, v64, v66
	v_fmac_f32_e32 v67, v72, v72
	v_add_f32_e32 v64, v67, v64
	v_add_f32_e32 v64, v80, v64
	v_mov_b32_e32 v251, v64
	s_nop 1
	v_permlane16_swap_b32_e32 v251, v65
	s_nop 1
	v_permlane16_swap_b32_e32 v65, v251
	v_cvt_pk_bf16_f32 v66, v68, v69
	v_cvt_pk_bf16_f32 v67, v70, v71
	v_cvt_pk_bf16_f32 v68, v74, v75
	v_cvt_pk_bf16_f32 v69, v72, v73
	s_waitcnt lgkmcnt(0)
	v_add_f32_e32 v64, v64, v65
	v_mov_b32_e32 v251, v64
	s_nop 1
	v_permlane32_swap_b32_e32 v251, v65
	s_nop 1
	v_permlane32_swap_b32_e32 v65, v251
	global_store_dwordx4 v[88:89], v[66:69], off offset:256
	s_and_saveexec_b64 s[40:41], s[6:7]
	s_cbranch_execz .LBB0_600
	s_waitcnt lgkmcnt(0)
	v_add_f32_e32 v64, v64, v65
	global_atomic_add_f32 v[112:113], v64, off offset:192
.LBB0_600:
	s_or_b64 exec, exec, s[40:41]
	v_add_co_u32_e32 v242, vcc, 0x140000, v244
	s_nop 1
	v_addc_co_u32_e32 v243, vcc, 0, v245, vcc
	global_load_dwordx4 v[208:211], v[242:243], off nt
	global_load_dwordx4 v[212:215], v[242:243], off offset:16 nt
	global_load_dwordx4 v[216:219], v[242:243], off offset:512 nt
	global_load_dwordx4 v[220:223], v[242:243], off offset:528 nt
	v_add_co_u32_e32 v240, vcc, 0x160000, v244
	s_nop 1
	v_addc_co_u32_e32 v241, vcc, 0, v245, vcc
	global_load_dwordx4 v[224:227], v[240:241], off nt
	global_load_dwordx4 v[228:231], v[240:241], off offset:16 nt
	global_load_dwordx4 v[232:235], v[240:241], off offset:512 nt
	global_load_dwordx4 v[236:239], v[240:241], off offset:528 nt
	v_lshl_add_u64 v[72:73], v[144:145], 0, s[22:23]
	v_lshl_add_u64 v[74:75], v[72:73], 2, s[10:11]
	s_waitcnt lgkmcnt(0)
	s_waitcnt vmcnt(15)
	s_nop 0
	v_mov_b32_e32 v64, v172
	v_mov_b32_e32 v65, v173
	v_mov_b32_e32 v66, v174
	v_mov_b32_e32 v67, v175
	s_waitcnt vmcnt(14)
	s_nop 0
	v_mov_b32_e32 v68, v176
	v_mov_b32_e32 v69, v177
	v_mov_b32_e32 v70, v178
	v_mov_b32_e32 v71, v179
	v_lshl_add_u64 v[72:73], v[72:73], 1, s[14:15]
	v_pk_add_f32 v[66:67], v[62:63], v[66:67]
	v_pk_add_f32 v[64:65], v[60:61], v[64:65]
	v_pk_add_f32 v[70:71], v[58:59], v[70:71]
	v_pk_add_f32 v[68:69], v[56:57], v[68:69]
	v_cvt_pk_bf16_f32 v56, v64, v65
	v_cvt_pk_bf16_f32 v57, v66, v67
	v_mul_f32_e32 v65, v65, v65
	v_cvt_pk_bf16_f32 v58, v68, v69
	v_cvt_pk_bf16_f32 v59, v70, v71
	global_store_dwordx4 v[72:73], v[56:59], off
	s_waitcnt vmcnt(13)
	s_nop 0
	v_mov_b32_e32 v56, v180
	v_mov_b32_e32 v57, v181
	v_mov_b32_e32 v58, v182
	v_mov_b32_e32 v59, v183
	s_nop 0
	s_waitcnt vmcnt(12)
	s_nop 0
	v_mov_b32_e32 v60, v184
	v_mov_b32_e32 v61, v185
	v_mov_b32_e32 v62, v186
	v_mov_b32_e32 v63, v187
	v_mul_f32_e32 v67, v67, v67
	v_mul_f32_e32 v69, v69, v69
	v_fmac_f32_e32 v65, v64, v64
	v_fmac_f32_e32 v67, v66, v66
	v_mul_f32_e32 v71, v71, v71
	v_fmac_f32_e32 v69, v68, v68
	v_add_f32_e32 v64, v65, v67
	v_fmac_f32_e32 v71, v70, v70
	v_add_f32_e32 v64, v64, v69
	v_add_f32_e32 v64, v71, v64
	v_pk_add_f32 v[54:55], v[54:55], v[58:59]
	v_pk_add_f32 v[52:53], v[52:53], v[56:57]
	v_pk_add_f32 v[58:59], v[48:49], v[60:61]
	v_mul_f32_e32 v48, v53, v53
	v_mul_f32_e32 v49, v55, v55
	v_pk_add_f32 v[56:57], v[50:51], v[62:63]
	v_mul_f32_e32 v50, v59, v59
	v_fmac_f32_e32 v48, v52, v52
	v_fmac_f32_e32 v49, v54, v54
	v_mul_f32_e32 v51, v57, v57
	v_fmac_f32_e32 v50, v58, v58
	v_add_f32_e32 v48, v48, v49
	v_add_f32_e32 v48, v48, v50
	v_fmac_f32_e32 v51, v56, v56
	v_add_f32_e32 v48, v51, v48
	v_add_f32_e32 v48, v64, v48
	v_mov_b32_e32 v251, v48
	s_nop 1
	v_permlane16_swap_b32_e32 v251, v49
	s_nop 1
	v_permlane16_swap_b32_e32 v49, v251
	v_cvt_pk_bf16_f32 v50, v52, v53
	v_cvt_pk_bf16_f32 v51, v54, v55
	v_cvt_pk_bf16_f32 v52, v58, v59
	v_cvt_pk_bf16_f32 v53, v56, v57
	s_waitcnt lgkmcnt(0)
	v_add_f32_e32 v48, v48, v49
	v_mov_b32_e32 v251, v48
	s_nop 1
	v_permlane32_swap_b32_e32 v251, v49
	s_nop 1
	v_permlane32_swap_b32_e32 v49, v251
	global_store_dwordx4 v[72:73], v[50:53], off offset:256
	s_and_saveexec_b64 s[40:41], s[6:7]
	s_cbranch_execz .LBB0_602
	s_waitcnt lgkmcnt(0)
	v_add_f32_e32 v48, v48, v49
	global_atomic_add_f32 v[112:113], v48, off offset:512
.LBB0_602:
	s_or_b64 exec, exec, s[40:41]
	v_lshl_add_u64 v[56:57], v[144:145], 0, s[24:25]
	v_lshl_add_u64 v[58:59], v[56:57], 2, s[10:11]
	s_waitcnt lgkmcnt(0)
	s_waitcnt vmcnt(11)
	s_nop 0
	v_mov_b32_e32 v48, v188
	v_mov_b32_e32 v49, v189
	v_mov_b32_e32 v50, v190
	v_mov_b32_e32 v51, v191
	s_waitcnt vmcnt(10)
	s_nop 0
	v_mov_b32_e32 v52, v196
	v_mov_b32_e32 v53, v197
	v_mov_b32_e32 v54, v198
	v_mov_b32_e32 v55, v199
	v_lshl_add_u64 v[56:57], v[56:57], 1, s[14:15]
	v_pk_add_f32 v[50:51], v[46:47], v[50:51]
	v_pk_add_f32 v[48:49], v[44:45], v[48:49]
	v_pk_add_f32 v[54:55], v[42:43], v[54:55]
	v_pk_add_f32 v[52:53], v[40:41], v[52:53]
	v_cvt_pk_bf16_f32 v40, v48, v49
	v_cvt_pk_bf16_f32 v41, v50, v51
	v_mul_f32_e32 v49, v49, v49
	v_cvt_pk_bf16_f32 v42, v52, v53
	v_cvt_pk_bf16_f32 v43, v54, v55
	global_store_dwordx4 v[56:57], v[40:43], off
	s_waitcnt vmcnt(9)
	s_nop 0
	v_mov_b32_e32 v40, v200
	v_mov_b32_e32 v41, v201
	v_mov_b32_e32 v42, v202
	v_mov_b32_e32 v43, v203
	s_nop 0
	s_waitcnt vmcnt(8)
	s_nop 0
	v_mov_b32_e32 v44, v204
	v_mov_b32_e32 v45, v205
	v_mov_b32_e32 v46, v206
	v_mov_b32_e32 v47, v207
	v_mul_f32_e32 v51, v51, v51
	v_mul_f32_e32 v53, v53, v53
	v_fmac_f32_e32 v49, v48, v48
	v_fmac_f32_e32 v51, v50, v50
	v_mul_f32_e32 v55, v55, v55
	v_fmac_f32_e32 v53, v52, v52
	v_add_f32_e32 v48, v49, v51
	v_fmac_f32_e32 v55, v54, v54
	v_add_f32_e32 v48, v48, v53
	v_add_f32_e32 v48, v55, v48
	v_pk_add_f32 v[38:39], v[38:39], v[42:43]
	v_pk_add_f32 v[36:37], v[36:37], v[40:41]
	v_pk_add_f32 v[42:43], v[32:33], v[44:45]
	v_mul_f32_e32 v32, v37, v37
	v_mul_f32_e32 v33, v39, v39
	v_pk_add_f32 v[40:41], v[34:35], v[46:47]
	v_mul_f32_e32 v34, v43, v43
	v_fmac_f32_e32 v32, v36, v36
	v_fmac_f32_e32 v33, v38, v38
	v_mul_f32_e32 v35, v41, v41
	v_fmac_f32_e32 v34, v42, v42
	v_add_f32_e32 v32, v32, v33
	v_add_f32_e32 v32, v32, v34
	v_fmac_f32_e32 v35, v40, v40
	v_add_f32_e32 v32, v35, v32
	v_add_f32_e32 v32, v48, v32
	v_mov_b32_e32 v251, v32
	s_nop 1
	v_permlane16_swap_b32_e32 v251, v33
	s_nop 1
	v_permlane16_swap_b32_e32 v33, v251
	v_cvt_pk_bf16_f32 v34, v36, v37
	v_cvt_pk_bf16_f32 v35, v38, v39
	v_cvt_pk_bf16_f32 v36, v42, v43
	v_cvt_pk_bf16_f32 v37, v40, v41
	s_waitcnt lgkmcnt(0)
	v_add_f32_e32 v32, v32, v33
	v_mov_b32_e32 v251, v32
	s_nop 1
	v_permlane32_swap_b32_e32 v251, v33
	s_nop 1
	v_permlane32_swap_b32_e32 v33, v251
	global_store_dwordx4 v[56:57], v[34:37], off offset:256
	s_and_saveexec_b64 s[40:41], s[6:7]
	s_cbranch_execz .LBB0_604
	s_waitcnt lgkmcnt(0)
	v_add_f32_e32 v32, v32, v33
	global_atomic_add_f32 v[112:113], v32, off offset:576
.LBB0_604:
	s_or_b64 exec, exec, s[40:41]
	v_lshl_add_u64 v[40:41], v[144:145], 0, s[26:27]
	v_lshl_add_u64 v[42:43], v[40:41], 2, s[10:11]
	s_waitcnt lgkmcnt(0)
	s_waitcnt vmcnt(7)
	s_nop 0
	v_mov_b32_e32 v32, v208
	v_mov_b32_e32 v33, v209
	v_mov_b32_e32 v34, v210
	v_mov_b32_e32 v35, v211
	s_waitcnt vmcnt(6)
	s_nop 0
	v_mov_b32_e32 v36, v212
	v_mov_b32_e32 v37, v213
	v_mov_b32_e32 v38, v214
	v_mov_b32_e32 v39, v215
	v_lshl_add_u64 v[40:41], v[40:41], 1, s[14:15]
	v_pk_add_f32 v[34:35], v[30:31], v[34:35]
	v_pk_add_f32 v[32:33], v[28:29], v[32:33]
	v_pk_add_f32 v[38:39], v[26:27], v[38:39]
	v_pk_add_f32 v[36:37], v[24:25], v[36:37]
	v_cvt_pk_bf16_f32 v24, v32, v33
	v_cvt_pk_bf16_f32 v25, v34, v35
	v_mul_f32_e32 v33, v33, v33
	v_cvt_pk_bf16_f32 v26, v36, v37
	v_cvt_pk_bf16_f32 v27, v38, v39
	global_store_dwordx4 v[40:41], v[24:27], off
	s_waitcnt vmcnt(5)
	s_nop 0
	v_mov_b32_e32 v24, v216
	v_mov_b32_e32 v25, v217
	v_mov_b32_e32 v26, v218
	v_mov_b32_e32 v27, v219
	s_nop 0
	s_waitcnt vmcnt(4)
	s_nop 0
	v_mov_b32_e32 v28, v220
	v_mov_b32_e32 v29, v221
	v_mov_b32_e32 v30, v222
	v_mov_b32_e32 v31, v223
	v_mul_f32_e32 v35, v35, v35
	v_mul_f32_e32 v37, v37, v37
	v_fmac_f32_e32 v33, v32, v32
	v_fmac_f32_e32 v35, v34, v34
	v_mul_f32_e32 v39, v39, v39
	v_fmac_f32_e32 v37, v36, v36
	v_add_f32_e32 v32, v33, v35
	v_fmac_f32_e32 v39, v38, v38
	v_add_f32_e32 v32, v32, v37
	v_add_f32_e32 v32, v39, v32
	v_pk_add_f32 v[22:23], v[22:23], v[26:27]
	v_pk_add_f32 v[20:21], v[20:21], v[24:25]
	v_pk_add_f32 v[26:27], v[16:17], v[28:29]
	v_mul_f32_e32 v16, v21, v21
	v_mul_f32_e32 v17, v23, v23
	v_pk_add_f32 v[24:25], v[18:19], v[30:31]
	v_mul_f32_e32 v18, v27, v27
	v_fmac_f32_e32 v16, v20, v20
	v_fmac_f32_e32 v17, v22, v22
	v_mul_f32_e32 v19, v25, v25
	v_fmac_f32_e32 v18, v26, v26
	v_add_f32_e32 v16, v16, v17
	v_add_f32_e32 v16, v16, v18
	v_fmac_f32_e32 v19, v24, v24
	v_add_f32_e32 v16, v19, v16
	v_add_f32_e32 v16, v32, v16
	v_mov_b32_e32 v251, v16
	s_nop 1
	v_permlane16_swap_b32_e32 v251, v17
	s_nop 1
	v_permlane16_swap_b32_e32 v17, v251
	v_cvt_pk_bf16_f32 v18, v20, v21
	v_cvt_pk_bf16_f32 v19, v22, v23
	v_cvt_pk_bf16_f32 v20, v26, v27
	v_cvt_pk_bf16_f32 v21, v24, v25
	s_waitcnt lgkmcnt(0)
	v_add_f32_e32 v16, v16, v17
	v_mov_b32_e32 v251, v16
	s_nop 1
	v_permlane32_swap_b32_e32 v251, v17
	s_nop 1
	v_permlane32_swap_b32_e32 v17, v251
	global_store_dwordx4 v[40:41], v[18:21], off offset:256
	s_and_saveexec_b64 s[40:41], s[6:7]
	s_cbranch_execz .LBB0_606
	s_waitcnt lgkmcnt(0)
	v_add_f32_e32 v16, v16, v17
	global_atomic_add_f32 v[112:113], v16, off offset:640
.LBB0_606:
	s_or_b64 exec, exec, s[40:41]
	v_lshl_add_u64 v[24:25], v[144:145], 0, s[28:29]
	v_lshl_add_u64 v[26:27], v[24:25], 2, s[10:11]
	s_waitcnt lgkmcnt(0)
	s_waitcnt vmcnt(3)
	s_nop 0
	v_mov_b32_e32 v16, v224
	v_mov_b32_e32 v17, v225
	v_mov_b32_e32 v18, v226
	v_mov_b32_e32 v19, v227
	s_waitcnt vmcnt(2)
	s_nop 0
	v_mov_b32_e32 v20, v228
	v_mov_b32_e32 v21, v229
	v_mov_b32_e32 v22, v230
	v_mov_b32_e32 v23, v231
	v_lshl_add_u64 v[24:25], v[24:25], 1, s[14:15]
	v_pk_add_f32 v[18:19], v[14:15], v[18:19]
	v_pk_add_f32 v[16:17], v[12:13], v[16:17]
	v_pk_add_f32 v[22:23], v[10:11], v[22:23]
	v_pk_add_f32 v[20:21], v[8:9], v[20:21]
	v_cvt_pk_bf16_f32 v8, v16, v17
	v_cvt_pk_bf16_f32 v9, v18, v19
	v_mul_f32_e32 v17, v17, v17
	v_cvt_pk_bf16_f32 v10, v20, v21
	v_cvt_pk_bf16_f32 v11, v22, v23
	global_store_dwordx4 v[24:25], v[8:11], off
	s_waitcnt vmcnt(1)
	s_nop 0
	v_mov_b32_e32 v8, v232
	v_mov_b32_e32 v9, v233
	v_mov_b32_e32 v10, v234
	v_mov_b32_e32 v11, v235
	s_nop 0
	s_waitcnt vmcnt(0)
	s_nop 0
	v_mov_b32_e32 v12, v236
	v_mov_b32_e32 v13, v237
	v_mov_b32_e32 v14, v238
	v_mov_b32_e32 v15, v239
	v_mul_f32_e32 v19, v19, v19
	v_mul_f32_e32 v21, v21, v21
	v_fmac_f32_e32 v17, v16, v16
	v_fmac_f32_e32 v19, v18, v18
	v_mul_f32_e32 v23, v23, v23
	v_fmac_f32_e32 v21, v20, v20
	v_add_f32_e32 v16, v17, v19
	v_fmac_f32_e32 v23, v22, v22
	v_add_f32_e32 v16, v16, v21
	v_add_f32_e32 v16, v23, v16
	v_pk_add_f32 v[6:7], v[6:7], v[10:11]
	v_pk_add_f32 v[4:5], v[4:5], v[8:9]
	v_pk_add_f32 v[10:11], v[0:1], v[12:13]
	v_mul_f32_e32 v0, v5, v5
	v_mul_f32_e32 v1, v7, v7
	v_pk_add_f32 v[8:9], v[2:3], v[14:15]
	v_mul_f32_e32 v2, v11, v11
	v_fmac_f32_e32 v0, v4, v4
	v_fmac_f32_e32 v1, v6, v6
	v_mul_f32_e32 v3, v9, v9
	v_fmac_f32_e32 v2, v10, v10
	v_add_f32_e32 v0, v0, v1
	v_add_f32_e32 v0, v0, v2
	v_fmac_f32_e32 v3, v8, v8
	v_add_f32_e32 v0, v3, v0
	v_add_f32_e32 v0, v16, v0
	v_mov_b32_e32 v251, v0
	s_nop 1
	v_permlane16_swap_b32_e32 v251, v1
	s_nop 1
	v_permlane16_swap_b32_e32 v1, v251
	v_cvt_pk_bf16_f32 v2, v4, v5
	v_cvt_pk_bf16_f32 v3, v6, v7
	v_cvt_pk_bf16_f32 v4, v10, v11
	v_cvt_pk_bf16_f32 v5, v8, v9
	s_waitcnt lgkmcnt(0)
	v_add_f32_e32 v0, v0, v1
	v_mov_b32_e32 v251, v0
	s_nop 1
	v_permlane32_swap_b32_e32 v251, v1
	s_nop 1
	v_permlane32_swap_b32_e32 v1, v251
	global_store_dwordx4 v[24:25], v[2:5], off offset:256
	s_and_saveexec_b64 s[40:41], s[6:7]
	s_cbranch_execz .LBB0_608
	s_waitcnt lgkmcnt(0)
	v_add_f32_e32 v0, v0, v1
	global_atomic_add_f32 v[112:113], v0, off offset:704

.LBB0_1190:
	s_waitcnt vmcnt(15)
	v_mov_b32_e32 v166, v180
	v_mov_b32_e32 v167, v181
	v_mov_b32_e32 v168, v182
	v_mov_b32_e32 v169, v183
	v_xor_b32_e32 v165, 32, v164
	v_lshlrev_b32_e32 v174, 16, v166
	v_and_b32_e32 v175, 0xffff0000, v166
	v_lshlrev_b32_e32 v166, 16, v167
	v_and_b32_e32 v167, 0xffff0000, v167
	v_lshlrev_b32_e32 v176, 16, v168
	v_and_b32_e32 v177, 0xffff0000, v168
	v_lshlrev_b32_e32 v168, 16, v169
	v_and_b32_e32 v169, 0xffff0000, v169
	v_pk_add_f32 v[126:127], v[126:127], v[166:167]
	v_pk_add_f32 v[174:175], v[124:125], v[174:175]
	v_pk_add_f32 v[178:179], v[122:123], v[168:169]
	v_pk_add_f32 v[176:177], v[120:121], v[176:177]
	v_cvt_pk_bf16_f32 v122, v174, v175
	v_cvt_pk_bf16_f32 v123, v126, v127
	v_and_b32_e32 v121, 64, v164
	v_cvt_pk_bf16_f32 v124, v176, v177
	v_cvt_pk_bf16_f32 v125, v178, v179
	s_waitcnt vmcnt(14)
	v_mov_b32_e32 v166, v184
	v_mov_b32_e32 v167, v185
	v_mov_b32_e32 v168, v186
	v_mov_b32_e32 v169, v187
	v_xor_b32_e32 v120, 16, v164
	v_add_u32_e32 v121, 64, v121
	v_cmp_lt_i32_e32 vcc, v120, v121
	v_mul_f32_e32 v127, v127, v127
	v_mul_f32_e32 v172, v177, v177
	v_cndmask_b32_e32 v120, v164, v120, vcc
	v_cmp_lt_i32_e32 vcc, v165, v121
	v_fmac_f32_e32 v127, v126, v126
	v_mul_f32_e32 v173, v179, v179
	v_cndmask_b32_e32 v121, v164, v165, vcc
	v_mul_f32_e32 v165, v175, v175
	v_fmac_f32_e32 v165, v174, v174
	v_fmac_f32_e32 v172, v176, v176
	v_add_f32_e32 v126, v165, v127
	v_fmac_f32_e32 v173, v178, v178
	v_add_f32_e32 v126, v172, v126
	v_add_f32_e32 v165, v173, v126
	v_lshlrev_b32_e32 v120, 2, v120
	v_lshlrev_b32_e32 v126, 16, v166
	v_and_b32_e32 v127, 0xffff0000, v166
	v_lshlrev_b32_e32 v166, 16, v167
	v_and_b32_e32 v167, 0xffff0000, v167
	v_lshlrev_b32_e32 v172, 16, v168
	v_and_b32_e32 v173, 0xffff0000, v168
	v_lshlrev_b32_e32 v168, 16, v169
	v_and_b32_e32 v169, 0xffff0000, v169
	v_pk_add_f32 v[118:119], v[118:119], v[166:167]
	v_pk_add_f32 v[116:117], v[116:117], v[126:127]
	v_pk_add_f32 v[126:127], v[114:115], v[168:169]
	v_pk_add_f32 v[112:113], v[112:113], v[172:173]
	v_mul_f32_e32 v114, v117, v117
	v_mul_f32_e32 v115, v119, v119
	v_mul_f32_e32 v166, v113, v113
	v_fmac_f32_e32 v114, v116, v116
	v_fmac_f32_e32 v115, v118, v118
	v_mul_f32_e32 v167, v127, v127
	v_fmac_f32_e32 v166, v112, v112
	v_add_f32_e32 v114, v114, v115
	v_fmac_f32_e32 v167, v126, v126
	v_add_f32_e32 v114, v166, v114
	v_add_f32_e32 v114, v167, v114
	v_add_f32_e32 v114, v165, v114
	v_mov_b32_e32 v251, v114
	s_nop 1
	v_permlane16_swap_b32_e32 v251, v115
	s_nop 1
	v_permlane16_swap_b32_e32 v115, v251
	v_lshl_add_u64 v[166:167], s[18:19], 0, v[170:171]
	global_store_dwordx4 v[166:167], v[122:125], off
	s_waitcnt lgkmcnt(0)
	v_add_f32_e32 v115, v114, v115
	v_lshlrev_b32_e32 v114, 2, v121
	v_cvt_pk_bf16_f32 v122, v116, v117
	v_mov_b32_e32 v251, v115
	s_nop 1
	v_permlane32_swap_b32_e32 v251, v116
	s_nop 1
	v_permlane32_swap_b32_e32 v116, v251
	v_cvt_pk_bf16_f32 v123, v118, v119
	v_cvt_pk_bf16_f32 v124, v112, v113
	v_lshl_add_u64 v[112:113], v[156:157], 2, s[20:21]
	v_cvt_pk_bf16_f32 v125, v126, v127
	global_store_dwordx4 v[166:167], v[122:125], off offset:256
	s_and_saveexec_b64 s[28:29], s[6:7]
	s_cbranch_execz .LBB0_1192
	s_waitcnt lgkmcnt(0)
	v_add_f32_e32 v115, v115, v116
	global_atomic_add_f32 v[112:113], v115, off
.LBB0_1192:
	s_or_b64 exec, exec, s[28:29]
	s_waitcnt lgkmcnt(0)
	v_or_b32_e32 v116, 16, v156
	v_ashrrev_i32_e32 v117, 31, v116
	v_lshlrev_b64 v[116:117], 11, v[116:117]
	v_lshl_add_u64 v[116:117], v[116:117], 0, v[154:155]
	v_lshlrev_b64 v[122:123], 1, v[116:117]
	v_lshl_add_u64 v[124:125], s[16:17], 0, v[122:123]
	s_waitcnt vmcnt(15)
	v_mov_b32_e32 v116, v188
	v_mov_b32_e32 v117, v189
	v_mov_b32_e32 v118, v190
	v_mov_b32_e32 v119, v191
	v_lshlrev_b32_e32 v126, 16, v116
	v_and_b32_e32 v127, 0xffff0000, v116
	v_lshlrev_b32_e32 v116, 16, v117
	v_and_b32_e32 v117, 0xffff0000, v117
	v_lshlrev_b32_e32 v166, 16, v118
	v_and_b32_e32 v167, 0xffff0000, v118
	v_lshlrev_b32_e32 v118, 16, v119
	v_and_b32_e32 v119, 0xffff0000, v119
	v_pk_add_f32 v[116:117], v[110:111], v[116:117]
	v_pk_add_f32 v[126:127], v[108:109], v[126:127]
	v_pk_add_f32 v[118:119], v[106:107], v[118:119]
	v_pk_add_f32 v[166:167], v[104:105], v[166:167]
	v_cvt_pk_bf16_f32 v104, v126, v127
	v_cvt_pk_bf16_f32 v105, v116, v117
	v_mul_f32_e32 v115, v127, v127
	v_cvt_pk_bf16_f32 v106, v166, v167
	v_cvt_pk_bf16_f32 v107, v118, v119
	s_waitcnt vmcnt(14)
	v_mov_b32_e32 v108, v194
	v_mov_b32_e32 v109, v195
	v_mov_b32_e32 v110, v196
	v_mov_b32_e32 v111, v197
	v_mul_f32_e32 v117, v117, v117
	v_mul_f32_e32 v121, v167, v167
	v_fmac_f32_e32 v115, v126, v126
	v_fmac_f32_e32 v117, v116, v116
	v_mul_f32_e32 v119, v119, v119
	v_fmac_f32_e32 v121, v166, v166
	v_add_f32_e32 v115, v115, v117
	v_fmac_f32_e32 v119, v118, v118
	v_add_f32_e32 v115, v121, v115
	v_add_f32_e32 v115, v119, v115
	v_lshlrev_b32_e32 v116, 16, v108
	v_and_b32_e32 v117, 0xffff0000, v108
	v_lshlrev_b32_e32 v108, 16, v109
	v_and_b32_e32 v109, 0xffff0000, v109
	v_lshlrev_b32_e32 v118, 16, v110
	v_and_b32_e32 v119, 0xffff0000, v110
	v_lshlrev_b32_e32 v110, 16, v111
	v_and_b32_e32 v111, 0xffff0000, v111
	v_pk_add_f32 v[102:103], v[102:103], v[108:109]
	v_pk_add_f32 v[100:101], v[100:101], v[116:117]
	v_pk_add_f32 v[108:109], v[98:99], v[110:111]
	v_pk_add_f32 v[110:111], v[96:97], v[118:119]
	v_mul_f32_e32 v96, v101, v101
	v_mul_f32_e32 v97, v103, v103
	v_mul_f32_e32 v98, v111, v111
	v_fmac_f32_e32 v96, v100, v100
	v_fmac_f32_e32 v97, v102, v102
	v_mul_f32_e32 v99, v109, v109
	v_fmac_f32_e32 v98, v110, v110
	v_add_f32_e32 v96, v96, v97
	v_add_f32_e32 v96, v98, v96
	v_fmac_f32_e32 v99, v108, v108
	v_add_f32_e32 v96, v99, v96
	v_add_f32_e32 v96, v115, v96
	v_mov_b32_e32 v251, v96
	s_nop 1
	v_permlane16_swap_b32_e32 v251, v97
	s_nop 1
	v_permlane16_swap_b32_e32 v97, v251
	v_lshl_add_u64 v[116:117], s[18:19], 0, v[122:123]
	global_store_dwordx4 v[116:117], v[104:107], off
	v_cvt_pk_bf16_f32 v98, v100, v101
	v_cvt_pk_bf16_f32 v99, v102, v103
	s_waitcnt lgkmcnt(0)
	v_add_f32_e32 v96, v96, v97
	v_mov_b32_e32 v251, v96
	s_nop 1
	v_permlane32_swap_b32_e32 v251, v97
	s_nop 1
	v_permlane32_swap_b32_e32 v97, v251
	v_cvt_pk_bf16_f32 v100, v110, v111
	v_cvt_pk_bf16_f32 v101, v108, v109
	global_store_dwordx4 v[116:117], v[98:101], off offset:256
	s_and_saveexec_b64 s[28:29], s[6:7]
	s_cbranch_execz .LBB0_1194
	s_waitcnt lgkmcnt(0)
	v_add_f32_e32 v96, v96, v97
	global_atomic_add_f32 v[112:113], v96, off offset:64
.LBB0_1194:
	s_or_b64 exec, exec, s[28:29]
	v_or_b32_e32 v96, 32, v156
	s_waitcnt lgkmcnt(0)
	v_ashrrev_i32_e32 v97, 31, v96
	v_lshlrev_b64 v[96:97], 11, v[96:97]
	v_lshl_add_u64 v[96:97], v[96:97], 0, v[154:155]
	v_lshlrev_b64 v[100:101], 1, v[96:97]
	v_lshl_add_u64 v[102:103], s[16:17], 0, v[100:101]
	s_waitcnt vmcnt(15)
	v_mov_b32_e32 v96, v198
	v_mov_b32_e32 v97, v199
	v_mov_b32_e32 v98, v200
	v_mov_b32_e32 v99, v201
	v_lshlrev_b32_e32 v104, 16, v96
	v_and_b32_e32 v105, 0xffff0000, v96
	v_lshlrev_b32_e32 v96, 16, v97
	v_and_b32_e32 v97, 0xffff0000, v97
	v_lshlrev_b32_e32 v106, 16, v98
	v_and_b32_e32 v107, 0xffff0000, v98
	v_lshlrev_b32_e32 v98, 16, v99
	v_and_b32_e32 v99, 0xffff0000, v99
	v_pk_add_f32 v[96:97], v[94:95], v[96:97]
	v_pk_add_f32 v[104:105], v[92:93], v[104:105]
	v_pk_add_f32 v[98:99], v[90:91], v[98:99]
	v_pk_add_f32 v[106:107], v[88:89], v[106:107]
	v_cvt_pk_bf16_f32 v88, v104, v105
	v_cvt_pk_bf16_f32 v89, v96, v97
	v_mul_f32_e32 v97, v97, v97
	v_cvt_pk_bf16_f32 v90, v106, v107
	v_cvt_pk_bf16_f32 v91, v98, v99
	s_waitcnt vmcnt(14)
	v_mov_b32_e32 v92, v202
	v_mov_b32_e32 v93, v203
	v_mov_b32_e32 v94, v204
	v_mov_b32_e32 v95, v205
	v_mul_f32_e32 v102, v105, v105
	v_mul_f32_e32 v103, v107, v107
	v_fmac_f32_e32 v102, v104, v104
	v_fmac_f32_e32 v97, v96, v96
	v_mul_f32_e32 v99, v99, v99
	v_fmac_f32_e32 v103, v106, v106
	v_add_f32_e32 v96, v102, v97
	v_fmac_f32_e32 v99, v98, v98
	v_add_f32_e32 v96, v103, v96
	v_add_f32_e32 v102, v99, v96
	v_lshlrev_b32_e32 v96, 16, v92
	v_and_b32_e32 v97, 0xffff0000, v92
	v_lshlrev_b32_e32 v92, 16, v93
	v_and_b32_e32 v93, 0xffff0000, v93
	v_lshlrev_b32_e32 v98, 16, v94
	v_and_b32_e32 v99, 0xffff0000, v94
	v_lshlrev_b32_e32 v94, 16, v95
	v_and_b32_e32 v95, 0xffff0000, v95
	v_pk_add_f32 v[86:87], v[86:87], v[92:93]
	v_pk_add_f32 v[84:85], v[84:85], v[96:97]
	v_pk_add_f32 v[92:93], v[82:83], v[94:95]
	v_pk_add_f32 v[94:95], v[80:81], v[98:99]
	v_mul_f32_e32 v80, v85, v85
	v_mul_f32_e32 v81, v87, v87
	v_mul_f32_e32 v82, v95, v95
	v_fmac_f32_e32 v80, v84, v84
	v_fmac_f32_e32 v81, v86, v86
	v_mul_f32_e32 v83, v93, v93
	v_fmac_f32_e32 v82, v94, v94
	v_add_f32_e32 v80, v80, v81
	v_add_f32_e32 v80, v82, v80
	v_fmac_f32_e32 v83, v92, v92
	v_add_f32_e32 v80, v83, v80
	v_add_f32_e32 v80, v102, v80
	v_mov_b32_e32 v251, v80
	s_nop 1
	v_permlane16_swap_b32_e32 v251, v81
	s_nop 1
	v_permlane16_swap_b32_e32 v81, v251
	v_lshl_add_u64 v[96:97], s[18:19], 0, v[100:101]
	global_store_dwordx4 v[96:97], v[88:91], off
	v_cvt_pk_bf16_f32 v82, v84, v85
	v_cvt_pk_bf16_f32 v83, v86, v87
	s_waitcnt lgkmcnt(0)
	v_add_f32_e32 v80, v80, v81
	v_mov_b32_e32 v251, v80
	s_nop 1
	v_permlane32_swap_b32_e32 v251, v81
	s_nop 1
	v_permlane32_swap_b32_e32 v81, v251
	v_cvt_pk_bf16_f32 v84, v94, v95
	v_cvt_pk_bf16_f32 v85, v92, v93
	global_store_dwordx4 v[96:97], v[82:85], off offset:256
	s_and_saveexec_b64 s[28:29], s[6:7]
	s_cbranch_execz .LBB0_1196
	s_waitcnt lgkmcnt(0)
	v_add_f32_e32 v80, v80, v81
	global_atomic_add_f32 v[112:113], v80, off offset:128
.LBB0_1196:
	s_or_b64 exec, exec, s[28:29]
	v_or_b32_e32 v80, 48, v156
	s_waitcnt lgkmcnt(0)
	v_ashrrev_i32_e32 v81, 31, v80
	v_lshlrev_b64 v[80:81], 11, v[80:81]
	v_lshl_add_u64 v[80:81], v[80:81], 0, v[154:155]
	v_lshlrev_b64 v[84:85], 1, v[80:81]
	v_lshl_add_u64 v[86:87], s[16:17], 0, v[84:85]
	s_waitcnt vmcnt(15)
	v_mov_b32_e32 v80, v206
	v_mov_b32_e32 v81, v207
	v_mov_b32_e32 v82, v208
	v_mov_b32_e32 v83, v209
	v_lshlrev_b32_e32 v88, 16, v80
	v_and_b32_e32 v89, 0xffff0000, v80
	v_lshlrev_b32_e32 v80, 16, v81
	v_and_b32_e32 v81, 0xffff0000, v81
	v_lshlrev_b32_e32 v90, 16, v82
	v_and_b32_e32 v91, 0xffff0000, v82
	v_lshlrev_b32_e32 v82, 16, v83
	v_and_b32_e32 v83, 0xffff0000, v83
	v_pk_add_f32 v[80:81], v[78:79], v[80:81]
	v_pk_add_f32 v[88:89], v[76:77], v[88:89]
	v_pk_add_f32 v[82:83], v[74:75], v[82:83]
	v_pk_add_f32 v[90:91], v[72:73], v[90:91]
	v_cvt_pk_bf16_f32 v72, v88, v89
	v_cvt_pk_bf16_f32 v73, v80, v81
	v_mul_f32_e32 v81, v81, v81
	v_cvt_pk_bf16_f32 v74, v90, v91
	v_cvt_pk_bf16_f32 v75, v82, v83
	s_waitcnt vmcnt(14)
	v_mov_b32_e32 v76, v210
	v_mov_b32_e32 v77, v211
	v_mov_b32_e32 v78, v212
	v_mov_b32_e32 v79, v213
	v_mul_f32_e32 v86, v89, v89
	v_mul_f32_e32 v87, v91, v91
	v_fmac_f32_e32 v86, v88, v88
	v_fmac_f32_e32 v81, v80, v80
	v_mul_f32_e32 v83, v83, v83
	v_fmac_f32_e32 v87, v90, v90
	v_add_f32_e32 v80, v86, v81
	v_fmac_f32_e32 v83, v82, v82
	v_add_f32_e32 v80, v87, v80
	v_add_f32_e32 v86, v83, v80
	v_lshlrev_b32_e32 v80, 16, v76
	v_and_b32_e32 v81, 0xffff0000, v76
	v_lshlrev_b32_e32 v76, 16, v77
	v_and_b32_e32 v77, 0xffff0000, v77
	v_lshlrev_b32_e32 v82, 16, v78
	v_and_b32_e32 v83, 0xffff0000, v78
	v_lshlrev_b32_e32 v78, 16, v79
	v_and_b32_e32 v79, 0xffff0000, v79
	v_pk_add_f32 v[70:71], v[70:71], v[76:77]
	v_pk_add_f32 v[68:69], v[68:69], v[80:81]
	v_pk_add_f32 v[76:77], v[66:67], v[78:79]
	v_pk_add_f32 v[78:79], v[64:65], v[82:83]
	v_mul_f32_e32 v64, v69, v69
	v_mul_f32_e32 v65, v71, v71
	v_mul_f32_e32 v66, v79, v79
	v_fmac_f32_e32 v64, v68, v68
	v_fmac_f32_e32 v65, v70, v70
	v_mul_f32_e32 v67, v77, v77
	v_fmac_f32_e32 v66, v78, v78
	v_add_f32_e32 v64, v64, v65
	v_add_f32_e32 v64, v66, v64
	v_fmac_f32_e32 v67, v76, v76
	v_add_f32_e32 v64, v67, v64
	v_add_f32_e32 v64, v86, v64
	v_mov_b32_e32 v251, v64
	s_nop 1
	v_permlane16_swap_b32_e32 v251, v65
	s_nop 1
	v_permlane16_swap_b32_e32 v65, v251
	v_lshl_add_u64 v[80:81], s[18:19], 0, v[84:85]
	global_store_dwordx4 v[80:81], v[72:75], off
	v_cvt_pk_bf16_f32 v66, v68, v69
	v_cvt_pk_bf16_f32 v67, v70, v71
	s_waitcnt lgkmcnt(0)
	v_add_f32_e32 v64, v64, v65
	v_mov_b32_e32 v251, v64
	s_nop 1
	v_permlane32_swap_b32_e32 v251, v65
	s_nop 1
	v_permlane32_swap_b32_e32 v65, v251
	v_cvt_pk_bf16_f32 v68, v78, v79
	v_cvt_pk_bf16_f32 v69, v76, v77
	global_store_dwordx4 v[80:81], v[66:69], off offset:256
	s_and_saveexec_b64 s[28:29], s[6:7]
	s_cbranch_execz .LBB0_1198
	s_waitcnt lgkmcnt(0)
	v_add_f32_e32 v64, v64, v65
	global_atomic_add_f32 v[112:113], v64, off offset:192
.LBB0_1198:
	s_or_b64 exec, exec, s[28:29]
	v_lshl_add_u64 v[68:69], v[152:153], 1, v[144:145]
	v_lshl_add_u64 v[70:71], s[16:17], 0, v[68:69]
	s_waitcnt lgkmcnt(0)
	s_waitcnt vmcnt(15)
	v_mov_b32_e32 v64, v214
	v_mov_b32_e32 v65, v215
	v_mov_b32_e32 v66, v216
	v_mov_b32_e32 v67, v217
	v_lshlrev_b32_e32 v72, 16, v64
	v_and_b32_e32 v73, 0xffff0000, v64
	v_lshlrev_b32_e32 v64, 16, v65
	v_and_b32_e32 v65, 0xffff0000, v65
	v_lshlrev_b32_e32 v74, 16, v66
	v_and_b32_e32 v75, 0xffff0000, v66
	v_lshlrev_b32_e32 v66, 16, v67
	v_and_b32_e32 v67, 0xffff0000, v67
	v_pk_add_f32 v[64:65], v[62:63], v[64:65]
	v_pk_add_f32 v[72:73], v[60:61], v[72:73]
	v_pk_add_f32 v[66:67], v[58:59], v[66:67]
	v_pk_add_f32 v[74:75], v[56:57], v[74:75]
	v_cvt_pk_bf16_f32 v56, v72, v73
	v_cvt_pk_bf16_f32 v57, v64, v65
	v_mul_f32_e32 v65, v65, v65
	v_cvt_pk_bf16_f32 v58, v74, v75
	v_cvt_pk_bf16_f32 v59, v66, v67
	s_waitcnt vmcnt(14)
	v_mov_b32_e32 v60, v218
	v_mov_b32_e32 v61, v219
	v_mov_b32_e32 v62, v220
	v_mov_b32_e32 v63, v221
	v_mul_f32_e32 v70, v73, v73
	v_mul_f32_e32 v71, v75, v75
	v_fmac_f32_e32 v70, v72, v72
	v_fmac_f32_e32 v65, v64, v64
	v_mul_f32_e32 v67, v67, v67
	v_fmac_f32_e32 v71, v74, v74
	v_add_f32_e32 v64, v70, v65
	v_fmac_f32_e32 v67, v66, v66
	v_add_f32_e32 v64, v71, v64
	v_add_f32_e32 v70, v67, v64
	v_lshlrev_b32_e32 v64, 16, v60
	v_and_b32_e32 v65, 0xffff0000, v60
	v_lshlrev_b32_e32 v60, 16, v61
	v_and_b32_e32 v61, 0xffff0000, v61
	v_lshlrev_b32_e32 v66, 16, v62
	v_and_b32_e32 v67, 0xffff0000, v62
	v_lshlrev_b32_e32 v62, 16, v63
	v_and_b32_e32 v63, 0xffff0000, v63
	v_pk_add_f32 v[54:55], v[54:55], v[60:61]
	v_pk_add_f32 v[52:53], v[52:53], v[64:65]
	v_pk_add_f32 v[60:61], v[50:51], v[62:63]
	v_pk_add_f32 v[62:63], v[48:49], v[66:67]
	v_mul_f32_e32 v48, v53, v53
	v_mul_f32_e32 v49, v55, v55
	v_mul_f32_e32 v50, v63, v63
	v_fmac_f32_e32 v48, v52, v52
	v_fmac_f32_e32 v49, v54, v54
	v_mul_f32_e32 v51, v61, v61
	v_fmac_f32_e32 v50, v62, v62
	v_add_f32_e32 v48, v48, v49
	v_add_f32_e32 v48, v50, v48
	v_fmac_f32_e32 v51, v60, v60
	v_add_f32_e32 v48, v51, v48
	v_add_f32_e32 v48, v70, v48
	v_mov_b32_e32 v251, v48
	s_nop 1
	v_permlane16_swap_b32_e32 v251, v49
	s_nop 1
	v_permlane16_swap_b32_e32 v49, v251
	v_lshl_add_u64 v[64:65], s[18:19], 0, v[68:69]
	global_store_dwordx4 v[64:65], v[56:59], off
	v_cvt_pk_bf16_f32 v50, v52, v53
	v_cvt_pk_bf16_f32 v51, v54, v55
	s_waitcnt lgkmcnt(0)
	v_add_f32_e32 v48, v48, v49
	v_mov_b32_e32 v251, v48
	s_nop 1
	v_permlane32_swap_b32_e32 v251, v49
	s_nop 1
	v_permlane32_swap_b32_e32 v49, v251
	v_cvt_pk_bf16_f32 v52, v62, v63
	v_cvt_pk_bf16_f32 v53, v60, v61
	global_store_dwordx4 v[64:65], v[50:53], off offset:256
	s_and_saveexec_b64 s[28:29], s[6:7]
	s_cbranch_execz .LBB0_1200
	s_waitcnt lgkmcnt(0)
	v_add_f32_e32 v48, v48, v49
	global_atomic_add_f32 v[112:113], v48, off offset:512
.LBB0_1200:
	s_or_b64 exec, exec, s[28:29]
	v_lshl_add_u64 v[52:53], v[152:153], 1, v[146:147]
	v_lshl_add_u64 v[54:55], s[16:17], 0, v[52:53]
	s_waitcnt lgkmcnt(0)
	s_waitcnt vmcnt(15)
	v_mov_b32_e32 v48, v222
	v_mov_b32_e32 v49, v223
	v_mov_b32_e32 v50, v224
	v_mov_b32_e32 v51, v225
	v_lshlrev_b32_e32 v56, 16, v48
	v_and_b32_e32 v57, 0xffff0000, v48
	v_lshlrev_b32_e32 v48, 16, v49
	v_and_b32_e32 v49, 0xffff0000, v49
	v_lshlrev_b32_e32 v58, 16, v50
	v_and_b32_e32 v59, 0xffff0000, v50
	v_lshlrev_b32_e32 v50, 16, v51
	v_and_b32_e32 v51, 0xffff0000, v51
	v_pk_add_f32 v[48:49], v[46:47], v[48:49]
	v_pk_add_f32 v[56:57], v[44:45], v[56:57]
	v_pk_add_f32 v[50:51], v[42:43], v[50:51]
	v_pk_add_f32 v[58:59], v[40:41], v[58:59]
	v_cvt_pk_bf16_f32 v40, v56, v57
	v_cvt_pk_bf16_f32 v41, v48, v49
	v_mul_f32_e32 v49, v49, v49
	v_cvt_pk_bf16_f32 v42, v58, v59
	v_cvt_pk_bf16_f32 v43, v50, v51
	s_waitcnt vmcnt(14)
	v_mov_b32_e32 v44, v226
	v_mov_b32_e32 v45, v227
	v_mov_b32_e32 v46, v228
	v_mov_b32_e32 v47, v229
	v_mul_f32_e32 v54, v57, v57
	v_mul_f32_e32 v55, v59, v59
	v_fmac_f32_e32 v54, v56, v56
	v_fmac_f32_e32 v49, v48, v48
	v_mul_f32_e32 v51, v51, v51
	v_fmac_f32_e32 v55, v58, v58
	v_add_f32_e32 v48, v54, v49
	v_fmac_f32_e32 v51, v50, v50
	v_add_f32_e32 v48, v55, v48
	v_add_f32_e32 v54, v51, v48
	v_lshlrev_b32_e32 v48, 16, v44
	v_and_b32_e32 v49, 0xffff0000, v44
	v_lshlrev_b32_e32 v44, 16, v45
	v_and_b32_e32 v45, 0xffff0000, v45
	v_lshlrev_b32_e32 v50, 16, v46
	v_and_b32_e32 v51, 0xffff0000, v46
	v_lshlrev_b32_e32 v46, 16, v47
	v_and_b32_e32 v47, 0xffff0000, v47
	v_pk_add_f32 v[38:39], v[38:39], v[44:45]
	v_pk_add_f32 v[36:37], v[36:37], v[48:49]
	v_pk_add_f32 v[44:45], v[34:35], v[46:47]
	v_pk_add_f32 v[46:47], v[32:33], v[50:51]
	v_mul_f32_e32 v32, v37, v37
	v_mul_f32_e32 v33, v39, v39
	v_mul_f32_e32 v34, v47, v47
	v_fmac_f32_e32 v32, v36, v36
	v_fmac_f32_e32 v33, v38, v38
	v_mul_f32_e32 v35, v45, v45
	v_fmac_f32_e32 v34, v46, v46
	v_add_f32_e32 v32, v32, v33
	v_add_f32_e32 v32, v34, v32
	v_fmac_f32_e32 v35, v44, v44
	v_add_f32_e32 v32, v35, v32
	v_add_f32_e32 v32, v54, v32
	v_mov_b32_e32 v251, v32
	s_nop 1
	v_permlane16_swap_b32_e32 v251, v33
	s_nop 1
	v_permlane16_swap_b32_e32 v33, v251
	v_lshl_add_u64 v[48:49], s[18:19], 0, v[52:53]
	global_store_dwordx4 v[48:49], v[40:43], off
	v_cvt_pk_bf16_f32 v34, v36, v37
	v_cvt_pk_bf16_f32 v35, v38, v39
	s_waitcnt lgkmcnt(0)
	v_add_f32_e32 v32, v32, v33
	v_mov_b32_e32 v251, v32
	s_nop 1
	v_permlane32_swap_b32_e32 v251, v33
	s_nop 1
	v_permlane32_swap_b32_e32 v33, v251
	v_cvt_pk_bf16_f32 v36, v46, v47
	v_cvt_pk_bf16_f32 v37, v44, v45
	global_store_dwordx4 v[48:49], v[34:37], off offset:256
	s_and_saveexec_b64 s[28:29], s[6:7]
	s_cbranch_execz .LBB0_1202
	s_waitcnt lgkmcnt(0)
	v_add_f32_e32 v32, v32, v33
	global_atomic_add_f32 v[112:113], v32, off offset:576
.LBB0_1202:
	s_or_b64 exec, exec, s[28:29]
	v_lshl_add_u64 v[36:37], v[152:153], 1, v[148:149]
	v_lshl_add_u64 v[38:39], s[16:17], 0, v[36:37]
	s_waitcnt lgkmcnt(0)
	s_waitcnt vmcnt(15)
	v_mov_b32_e32 v32, v230
	v_mov_b32_e32 v33, v231
	v_mov_b32_e32 v34, v232
	v_mov_b32_e32 v35, v233
	v_lshlrev_b32_e32 v40, 16, v32
	v_and_b32_e32 v41, 0xffff0000, v32
	v_lshlrev_b32_e32 v32, 16, v33
	v_and_b32_e32 v33, 0xffff0000, v33
	v_lshlrev_b32_e32 v42, 16, v34
	v_and_b32_e32 v43, 0xffff0000, v34
	v_lshlrev_b32_e32 v34, 16, v35
	v_and_b32_e32 v35, 0xffff0000, v35
	v_pk_add_f32 v[32:33], v[30:31], v[32:33]
	v_pk_add_f32 v[40:41], v[28:29], v[40:41]
	v_pk_add_f32 v[34:35], v[26:27], v[34:35]
	v_pk_add_f32 v[42:43], v[24:25], v[42:43]
	v_cvt_pk_bf16_f32 v24, v40, v41
	v_cvt_pk_bf16_f32 v25, v32, v33
	v_mul_f32_e32 v33, v33, v33
	v_cvt_pk_bf16_f32 v26, v42, v43
	v_cvt_pk_bf16_f32 v27, v34, v35
	s_waitcnt vmcnt(14)
	v_mov_b32_e32 v28, v234
	v_mov_b32_e32 v29, v235
	v_mov_b32_e32 v30, v236
	v_mov_b32_e32 v31, v237
	v_mul_f32_e32 v38, v41, v41
	v_mul_f32_e32 v39, v43, v43
	v_fmac_f32_e32 v38, v40, v40
	v_fmac_f32_e32 v33, v32, v32
	v_mul_f32_e32 v35, v35, v35
	v_fmac_f32_e32 v39, v42, v42
	v_add_f32_e32 v32, v38, v33
	v_fmac_f32_e32 v35, v34, v34
	v_add_f32_e32 v32, v39, v32
	v_add_f32_e32 v38, v35, v32
	v_lshlrev_b32_e32 v32, 16, v28
	v_and_b32_e32 v33, 0xffff0000, v28
	v_lshlrev_b32_e32 v28, 16, v29
	v_and_b32_e32 v29, 0xffff0000, v29
	v_lshlrev_b32_e32 v34, 16, v30
	v_and_b32_e32 v35, 0xffff0000, v30
	v_lshlrev_b32_e32 v30, 16, v31
	v_and_b32_e32 v31, 0xffff0000, v31
	v_pk_add_f32 v[22:23], v[22:23], v[28:29]
	v_pk_add_f32 v[20:21], v[20:21], v[32:33]
	v_pk_add_f32 v[28:29], v[18:19], v[30:31]
	v_pk_add_f32 v[30:31], v[16:17], v[34:35]
	v_mul_f32_e32 v16, v21, v21
	v_mul_f32_e32 v17, v23, v23
	v_mul_f32_e32 v18, v31, v31
	v_fmac_f32_e32 v16, v20, v20
	v_fmac_f32_e32 v17, v22, v22
	v_mul_f32_e32 v19, v29, v29
	v_fmac_f32_e32 v18, v30, v30
	v_add_f32_e32 v16, v16, v17
	v_add_f32_e32 v16, v18, v16
	v_fmac_f32_e32 v19, v28, v28
	v_add_f32_e32 v16, v19, v16
	v_add_f32_e32 v16, v38, v16
	v_mov_b32_e32 v251, v16
	s_nop 1
	v_permlane16_swap_b32_e32 v251, v17
	s_nop 1
	v_permlane16_swap_b32_e32 v17, v251
	v_lshl_add_u64 v[32:33], s[18:19], 0, v[36:37]
	global_store_dwordx4 v[32:33], v[24:27], off
	v_cvt_pk_bf16_f32 v18, v20, v21
	v_cvt_pk_bf16_f32 v19, v22, v23
	s_waitcnt lgkmcnt(0)
	v_add_f32_e32 v16, v16, v17
	v_mov_b32_e32 v251, v16
	s_nop 1
	v_permlane32_swap_b32_e32 v251, v17
	s_nop 1
	v_permlane32_swap_b32_e32 v17, v251
	v_cvt_pk_bf16_f32 v20, v30, v31
	v_cvt_pk_bf16_f32 v21, v28, v29
	global_store_dwordx4 v[32:33], v[18:21], off offset:256
	s_and_saveexec_b64 s[28:29], s[6:7]
	s_cbranch_execz .LBB0_1204
	s_waitcnt lgkmcnt(0)
	v_add_f32_e32 v16, v16, v17
	global_atomic_add_f32 v[112:113], v16, off offset:640
.LBB0_1204:
	s_or_b64 exec, exec, s[28:29]
	v_lshl_add_u64 v[20:21], v[152:153], 1, v[150:151]
	v_lshl_add_u64 v[22:23], s[16:17], 0, v[20:21]
	s_waitcnt lgkmcnt(0)
	s_waitcnt vmcnt(15)
	v_mov_b32_e32 v16, v238
	v_mov_b32_e32 v17, v239
	v_mov_b32_e32 v18, v240
	v_mov_b32_e32 v19, v241
	v_lshlrev_b32_e32 v24, 16, v16
	v_and_b32_e32 v25, 0xffff0000, v16
	v_lshlrev_b32_e32 v16, 16, v17
	v_and_b32_e32 v17, 0xffff0000, v17
	v_lshlrev_b32_e32 v26, 16, v18
	v_and_b32_e32 v27, 0xffff0000, v18
	v_lshlrev_b32_e32 v18, 16, v19
	v_and_b32_e32 v19, 0xffff0000, v19
	v_pk_add_f32 v[16:17], v[14:15], v[16:17]
	v_pk_add_f32 v[24:25], v[12:13], v[24:25]
	v_pk_add_f32 v[18:19], v[10:11], v[18:19]
	v_pk_add_f32 v[26:27], v[8:9], v[26:27]
	v_cvt_pk_bf16_f32 v8, v24, v25
	v_cvt_pk_bf16_f32 v9, v16, v17
	v_mul_f32_e32 v17, v17, v17
	v_cvt_pk_bf16_f32 v10, v26, v27
	v_cvt_pk_bf16_f32 v11, v18, v19
	s_waitcnt vmcnt(14)
	v_mov_b32_e32 v12, v242
	v_mov_b32_e32 v13, v243
	v_mov_b32_e32 v14, v244
	v_mov_b32_e32 v15, v245
	v_mul_f32_e32 v22, v25, v25
	v_mul_f32_e32 v23, v27, v27
	v_fmac_f32_e32 v22, v24, v24
	v_fmac_f32_e32 v17, v16, v16
	v_mul_f32_e32 v19, v19, v19
	v_fmac_f32_e32 v23, v26, v26
	v_add_f32_e32 v16, v22, v17
	v_fmac_f32_e32 v19, v18, v18
	v_add_f32_e32 v16, v23, v16
	v_add_f32_e32 v22, v19, v16
	v_lshlrev_b32_e32 v16, 16, v12
	v_and_b32_e32 v17, 0xffff0000, v12
	v_lshlrev_b32_e32 v12, 16, v13
	v_and_b32_e32 v13, 0xffff0000, v13
	v_lshlrev_b32_e32 v18, 16, v14
	v_and_b32_e32 v19, 0xffff0000, v14
	v_lshlrev_b32_e32 v14, 16, v15
	v_and_b32_e32 v15, 0xffff0000, v15
	v_pk_add_f32 v[6:7], v[6:7], v[12:13]
	v_pk_add_f32 v[4:5], v[4:5], v[16:17]
	v_pk_add_f32 v[12:13], v[2:3], v[14:15]
	v_pk_add_f32 v[14:15], v[0:1], v[18:19]
	v_mul_f32_e32 v0, v5, v5
	v_mul_f32_e32 v1, v7, v7
	v_mul_f32_e32 v2, v15, v15
	v_fmac_f32_e32 v0, v4, v4
	v_fmac_f32_e32 v1, v6, v6
	v_mul_f32_e32 v3, v13, v13
	v_fmac_f32_e32 v2, v14, v14
	v_add_f32_e32 v0, v0, v1
	v_add_f32_e32 v0, v2, v0
	v_fmac_f32_e32 v3, v12, v12
	v_add_f32_e32 v0, v3, v0
	v_add_f32_e32 v0, v22, v0
	v_mov_b32_e32 v251, v0
	s_nop 1
	v_permlane16_swap_b32_e32 v251, v1
	s_nop 1
	v_permlane16_swap_b32_e32 v1, v251
	v_lshl_add_u64 v[16:17], s[18:19], 0, v[20:21]
	global_store_dwordx4 v[16:17], v[8:11], off
	v_cvt_pk_bf16_f32 v2, v4, v5
	v_cvt_pk_bf16_f32 v3, v6, v7
	s_waitcnt lgkmcnt(0)
	v_add_f32_e32 v0, v0, v1
	v_mov_b32_e32 v251, v0
	s_nop 1
	v_permlane32_swap_b32_e32 v251, v1
	s_nop 1
	v_permlane32_swap_b32_e32 v1, v251
	v_cvt_pk_bf16_f32 v4, v14, v15
	v_cvt_pk_bf16_f32 v5, v12, v13
	global_store_dwordx4 v[16:17], v[2:5], off offset:256
	s_and_saveexec_b64 s[28:29], s[6:7]
	s_cbranch_execz .LBB0_1206
	s_waitcnt lgkmcnt(0)
	v_add_f32_e32 v0, v0, v1
	global_atomic_add_f32 v[112:113], v0, off offset:704

.LBB0_1423:
	s_waitcnt vmcnt(15)
	v_mov_b32_e32 v166, v180
	v_mov_b32_e32 v167, v181
	v_mov_b32_e32 v168, v182
	v_mov_b32_e32 v169, v183
	v_xor_b32_e32 v165, 32, v164
	v_lshlrev_b32_e32 v174, 16, v166
	v_and_b32_e32 v175, 0xffff0000, v166
	v_lshlrev_b32_e32 v166, 16, v167
	v_and_b32_e32 v167, 0xffff0000, v167
	v_lshlrev_b32_e32 v176, 16, v168
	v_and_b32_e32 v177, 0xffff0000, v168
	v_lshlrev_b32_e32 v168, 16, v169
	v_and_b32_e32 v169, 0xffff0000, v169
	v_pk_add_f32 v[126:127], v[126:127], v[166:167]
	v_pk_add_f32 v[174:175], v[124:125], v[174:175]
	v_pk_add_f32 v[178:179], v[122:123], v[168:169]
	v_pk_add_f32 v[176:177], v[120:121], v[176:177]
	v_cvt_pk_bf16_f32 v122, v174, v175
	v_cvt_pk_bf16_f32 v123, v126, v127
	v_and_b32_e32 v121, 64, v164
	v_cvt_pk_bf16_f32 v124, v176, v177
	v_cvt_pk_bf16_f32 v125, v178, v179
	s_waitcnt vmcnt(14)
	v_mov_b32_e32 v166, v184
	v_mov_b32_e32 v167, v185
	v_mov_b32_e32 v168, v186
	v_mov_b32_e32 v169, v187
	v_xor_b32_e32 v120, 16, v164
	v_add_u32_e32 v121, 64, v121
	v_cmp_lt_i32_e32 vcc, v120, v121
	v_mul_f32_e32 v127, v127, v127
	v_mul_f32_e32 v172, v177, v177
	v_cndmask_b32_e32 v120, v164, v120, vcc
	v_cmp_lt_i32_e32 vcc, v165, v121
	v_fmac_f32_e32 v127, v126, v126
	v_mul_f32_e32 v173, v179, v179
	v_cndmask_b32_e32 v121, v164, v165, vcc
	v_mul_f32_e32 v165, v175, v175
	v_fmac_f32_e32 v165, v174, v174
	v_fmac_f32_e32 v172, v176, v176
	v_add_f32_e32 v126, v165, v127
	v_fmac_f32_e32 v173, v178, v178
	v_add_f32_e32 v126, v172, v126
	v_add_f32_e32 v165, v173, v126
	v_lshlrev_b32_e32 v120, 2, v120
	v_lshlrev_b32_e32 v126, 16, v166
	v_and_b32_e32 v127, 0xffff0000, v166
	v_lshlrev_b32_e32 v166, 16, v167
	v_and_b32_e32 v167, 0xffff0000, v167
	v_lshlrev_b32_e32 v172, 16, v168
	v_and_b32_e32 v173, 0xffff0000, v168
	v_lshlrev_b32_e32 v168, 16, v169
	v_and_b32_e32 v169, 0xffff0000, v169
	v_pk_add_f32 v[118:119], v[118:119], v[166:167]
	v_pk_add_f32 v[116:117], v[116:117], v[126:127]
	v_pk_add_f32 v[126:127], v[114:115], v[168:169]
	v_pk_add_f32 v[112:113], v[112:113], v[172:173]
	v_mul_f32_e32 v114, v117, v117
	v_mul_f32_e32 v115, v119, v119
	v_mul_f32_e32 v166, v113, v113
	v_fmac_f32_e32 v114, v116, v116
	v_fmac_f32_e32 v115, v118, v118
	v_mul_f32_e32 v167, v127, v127
	v_fmac_f32_e32 v166, v112, v112
	v_add_f32_e32 v114, v114, v115
	v_fmac_f32_e32 v167, v126, v126
	v_add_f32_e32 v114, v166, v114
	v_add_f32_e32 v114, v167, v114
	v_add_f32_e32 v114, v165, v114
	v_mov_b32_e32 v251, v114
	s_nop 1
	v_permlane16_swap_b32_e32 v251, v115
	s_nop 1
	v_permlane16_swap_b32_e32 v115, v251
	v_lshl_add_u64 v[166:167], s[16:17], 0, v[170:171]
	global_store_dwordx4 v[166:167], v[122:125], off
	s_waitcnt lgkmcnt(0)
	v_add_f32_e32 v115, v114, v115
	v_lshlrev_b32_e32 v114, 2, v121
	v_cvt_pk_bf16_f32 v122, v116, v117
	v_mov_b32_e32 v251, v115
	s_nop 1
	v_permlane32_swap_b32_e32 v251, v116
	s_nop 1
	v_permlane32_swap_b32_e32 v116, v251
	v_cvt_pk_bf16_f32 v123, v118, v119
	v_cvt_pk_bf16_f32 v124, v112, v113
	v_lshl_add_u64 v[112:113], v[156:157], 2, s[18:19]
	v_cvt_pk_bf16_f32 v125, v126, v127
	global_store_dwordx4 v[166:167], v[122:125], off offset:256
	s_and_saveexec_b64 s[34:35], s[6:7]
	s_cbranch_execz .LBB0_1425
	s_waitcnt lgkmcnt(0)
	v_add_f32_e32 v115, v115, v116
	global_atomic_add_f32 v[112:113], v115, off
.LBB0_1425:
	s_or_b64 exec, exec, s[34:35]
	s_waitcnt lgkmcnt(0)
	v_or_b32_e32 v116, 16, v156
	v_ashrrev_i32_e32 v117, 31, v116
	v_lshlrev_b64 v[116:117], 11, v[116:117]
	v_lshl_add_u64 v[116:117], v[116:117], 0, v[154:155]
	v_lshlrev_b64 v[122:123], 1, v[116:117]
	v_lshl_add_u64 v[124:125], s[12:13], 0, v[122:123]
	s_waitcnt vmcnt(15)
	v_mov_b32_e32 v116, v188
	v_mov_b32_e32 v117, v189
	v_mov_b32_e32 v118, v190
	v_mov_b32_e32 v119, v191
	v_lshlrev_b32_e32 v126, 16, v116
	v_and_b32_e32 v127, 0xffff0000, v116
	v_lshlrev_b32_e32 v116, 16, v117
	v_and_b32_e32 v117, 0xffff0000, v117
	v_lshlrev_b32_e32 v166, 16, v118
	v_and_b32_e32 v167, 0xffff0000, v118
	v_lshlrev_b32_e32 v118, 16, v119
	v_and_b32_e32 v119, 0xffff0000, v119
	v_pk_add_f32 v[116:117], v[110:111], v[116:117]
	v_pk_add_f32 v[126:127], v[108:109], v[126:127]
	v_pk_add_f32 v[118:119], v[106:107], v[118:119]
	v_pk_add_f32 v[166:167], v[104:105], v[166:167]
	v_cvt_pk_bf16_f32 v104, v126, v127
	v_cvt_pk_bf16_f32 v105, v116, v117
	v_mul_f32_e32 v115, v127, v127
	v_cvt_pk_bf16_f32 v106, v166, v167
	v_cvt_pk_bf16_f32 v107, v118, v119
	s_waitcnt vmcnt(14)
	v_mov_b32_e32 v108, v194
	v_mov_b32_e32 v109, v195
	v_mov_b32_e32 v110, v196
	v_mov_b32_e32 v111, v197
	v_mul_f32_e32 v117, v117, v117
	v_mul_f32_e32 v121, v167, v167
	v_fmac_f32_e32 v115, v126, v126
	v_fmac_f32_e32 v117, v116, v116
	v_mul_f32_e32 v119, v119, v119
	v_fmac_f32_e32 v121, v166, v166
	v_add_f32_e32 v115, v115, v117
	v_fmac_f32_e32 v119, v118, v118
	v_add_f32_e32 v115, v121, v115
	v_add_f32_e32 v115, v119, v115
	v_lshlrev_b32_e32 v116, 16, v108
	v_and_b32_e32 v117, 0xffff0000, v108
	v_lshlrev_b32_e32 v108, 16, v109
	v_and_b32_e32 v109, 0xffff0000, v109
	v_lshlrev_b32_e32 v118, 16, v110
	v_and_b32_e32 v119, 0xffff0000, v110
	v_lshlrev_b32_e32 v110, 16, v111
	v_and_b32_e32 v111, 0xffff0000, v111
	v_pk_add_f32 v[102:103], v[102:103], v[108:109]
	v_pk_add_f32 v[100:101], v[100:101], v[116:117]
	v_pk_add_f32 v[108:109], v[98:99], v[110:111]
	v_pk_add_f32 v[110:111], v[96:97], v[118:119]
	v_mul_f32_e32 v96, v101, v101
	v_mul_f32_e32 v97, v103, v103
	v_mul_f32_e32 v98, v111, v111
	v_fmac_f32_e32 v96, v100, v100
	v_fmac_f32_e32 v97, v102, v102
	v_mul_f32_e32 v99, v109, v109
	v_fmac_f32_e32 v98, v110, v110
	v_add_f32_e32 v96, v96, v97
	v_add_f32_e32 v96, v98, v96
	v_fmac_f32_e32 v99, v108, v108
	v_add_f32_e32 v96, v99, v96
	v_add_f32_e32 v96, v115, v96
	v_mov_b32_e32 v251, v96
	s_nop 1
	v_permlane16_swap_b32_e32 v251, v97
	s_nop 1
	v_permlane16_swap_b32_e32 v97, v251
	v_lshl_add_u64 v[116:117], s[16:17], 0, v[122:123]
	global_store_dwordx4 v[116:117], v[104:107], off
	v_cvt_pk_bf16_f32 v98, v100, v101
	v_cvt_pk_bf16_f32 v99, v102, v103
	s_waitcnt lgkmcnt(0)
	v_add_f32_e32 v96, v96, v97
	v_mov_b32_e32 v251, v96
	s_nop 1
	v_permlane32_swap_b32_e32 v251, v97
	s_nop 1
	v_permlane32_swap_b32_e32 v97, v251
	v_cvt_pk_bf16_f32 v100, v110, v111
	v_cvt_pk_bf16_f32 v101, v108, v109
	global_store_dwordx4 v[116:117], v[98:101], off offset:256
	s_and_saveexec_b64 s[34:35], s[6:7]
	s_cbranch_execz .LBB0_1427
	s_waitcnt lgkmcnt(0)
	v_add_f32_e32 v96, v96, v97
	global_atomic_add_f32 v[112:113], v96, off offset:64
.LBB0_1427:
	s_or_b64 exec, exec, s[34:35]
	v_or_b32_e32 v96, 32, v156
	s_waitcnt lgkmcnt(0)
	v_ashrrev_i32_e32 v97, 31, v96
	v_lshlrev_b64 v[96:97], 11, v[96:97]
	v_lshl_add_u64 v[96:97], v[96:97], 0, v[154:155]
	v_lshlrev_b64 v[100:101], 1, v[96:97]
	v_lshl_add_u64 v[102:103], s[12:13], 0, v[100:101]
	s_waitcnt vmcnt(15)
	v_mov_b32_e32 v96, v198
	v_mov_b32_e32 v97, v199
	v_mov_b32_e32 v98, v200
	v_mov_b32_e32 v99, v201
	v_lshlrev_b32_e32 v104, 16, v96
	v_and_b32_e32 v105, 0xffff0000, v96
	v_lshlrev_b32_e32 v96, 16, v97
	v_and_b32_e32 v97, 0xffff0000, v97
	v_lshlrev_b32_e32 v106, 16, v98
	v_and_b32_e32 v107, 0xffff0000, v98
	v_lshlrev_b32_e32 v98, 16, v99
	v_and_b32_e32 v99, 0xffff0000, v99
	v_pk_add_f32 v[96:97], v[94:95], v[96:97]
	v_pk_add_f32 v[104:105], v[92:93], v[104:105]
	v_pk_add_f32 v[98:99], v[90:91], v[98:99]
	v_pk_add_f32 v[106:107], v[88:89], v[106:107]
	v_cvt_pk_bf16_f32 v88, v104, v105
	v_cvt_pk_bf16_f32 v89, v96, v97
	v_mul_f32_e32 v97, v97, v97
	v_cvt_pk_bf16_f32 v90, v106, v107
	v_cvt_pk_bf16_f32 v91, v98, v99
	s_waitcnt vmcnt(14)
	v_mov_b32_e32 v92, v202
	v_mov_b32_e32 v93, v203
	v_mov_b32_e32 v94, v204
	v_mov_b32_e32 v95, v205
	v_mul_f32_e32 v102, v105, v105
	v_mul_f32_e32 v103, v107, v107
	v_fmac_f32_e32 v102, v104, v104
	v_fmac_f32_e32 v97, v96, v96
	v_mul_f32_e32 v99, v99, v99
	v_fmac_f32_e32 v103, v106, v106
	v_add_f32_e32 v96, v102, v97
	v_fmac_f32_e32 v99, v98, v98
	v_add_f32_e32 v96, v103, v96
	v_add_f32_e32 v102, v99, v96
	v_lshlrev_b32_e32 v96, 16, v92
	v_and_b32_e32 v97, 0xffff0000, v92
	v_lshlrev_b32_e32 v92, 16, v93
	v_and_b32_e32 v93, 0xffff0000, v93
	v_lshlrev_b32_e32 v98, 16, v94
	v_and_b32_e32 v99, 0xffff0000, v94
	v_lshlrev_b32_e32 v94, 16, v95
	v_and_b32_e32 v95, 0xffff0000, v95
	v_pk_add_f32 v[86:87], v[86:87], v[92:93]
	v_pk_add_f32 v[84:85], v[84:85], v[96:97]
	v_pk_add_f32 v[92:93], v[82:83], v[94:95]
	v_pk_add_f32 v[94:95], v[80:81], v[98:99]
	v_mul_f32_e32 v80, v85, v85
	v_mul_f32_e32 v81, v87, v87
	v_mul_f32_e32 v82, v95, v95
	v_fmac_f32_e32 v80, v84, v84
	v_fmac_f32_e32 v81, v86, v86
	v_mul_f32_e32 v83, v93, v93
	v_fmac_f32_e32 v82, v94, v94
	v_add_f32_e32 v80, v80, v81
	v_add_f32_e32 v80, v82, v80
	v_fmac_f32_e32 v83, v92, v92
	v_add_f32_e32 v80, v83, v80
	v_add_f32_e32 v80, v102, v80
	v_mov_b32_e32 v251, v80
	s_nop 1
	v_permlane16_swap_b32_e32 v251, v81
	s_nop 1
	v_permlane16_swap_b32_e32 v81, v251
	v_lshl_add_u64 v[96:97], s[16:17], 0, v[100:101]
	global_store_dwordx4 v[96:97], v[88:91], off
	v_cvt_pk_bf16_f32 v82, v84, v85
	v_cvt_pk_bf16_f32 v83, v86, v87
	s_waitcnt lgkmcnt(0)
	v_add_f32_e32 v80, v80, v81
	v_mov_b32_e32 v251, v80
	s_nop 1
	v_permlane32_swap_b32_e32 v251, v81
	s_nop 1
	v_permlane32_swap_b32_e32 v81, v251
	v_cvt_pk_bf16_f32 v84, v94, v95
	v_cvt_pk_bf16_f32 v85, v92, v93
	global_store_dwordx4 v[96:97], v[82:85], off offset:256
	s_and_saveexec_b64 s[34:35], s[6:7]
	s_cbranch_execz .LBB0_1429
	s_waitcnt lgkmcnt(0)
	v_add_f32_e32 v80, v80, v81
	global_atomic_add_f32 v[112:113], v80, off offset:128
.LBB0_1429:
	s_or_b64 exec, exec, s[34:35]
	v_or_b32_e32 v80, 48, v156
	s_waitcnt lgkmcnt(0)
	v_ashrrev_i32_e32 v81, 31, v80
	v_lshlrev_b64 v[80:81], 11, v[80:81]
	v_lshl_add_u64 v[80:81], v[80:81], 0, v[154:155]
	v_lshlrev_b64 v[84:85], 1, v[80:81]
	v_lshl_add_u64 v[86:87], s[12:13], 0, v[84:85]
	s_waitcnt vmcnt(15)
	v_mov_b32_e32 v80, v206
	v_mov_b32_e32 v81, v207
	v_mov_b32_e32 v82, v208
	v_mov_b32_e32 v83, v209
	v_lshlrev_b32_e32 v88, 16, v80
	v_and_b32_e32 v89, 0xffff0000, v80
	v_lshlrev_b32_e32 v80, 16, v81
	v_and_b32_e32 v81, 0xffff0000, v81
	v_lshlrev_b32_e32 v90, 16, v82
	v_and_b32_e32 v91, 0xffff0000, v82
	v_lshlrev_b32_e32 v82, 16, v83
	v_and_b32_e32 v83, 0xffff0000, v83
	v_pk_add_f32 v[80:81], v[78:79], v[80:81]
	v_pk_add_f32 v[88:89], v[76:77], v[88:89]
	v_pk_add_f32 v[82:83], v[74:75], v[82:83]
	v_pk_add_f32 v[90:91], v[72:73], v[90:91]
	v_cvt_pk_bf16_f32 v72, v88, v89
	v_cvt_pk_bf16_f32 v73, v80, v81
	v_mul_f32_e32 v81, v81, v81
	v_cvt_pk_bf16_f32 v74, v90, v91
	v_cvt_pk_bf16_f32 v75, v82, v83
	s_waitcnt vmcnt(14)
	v_mov_b32_e32 v76, v210
	v_mov_b32_e32 v77, v211
	v_mov_b32_e32 v78, v212
	v_mov_b32_e32 v79, v213
	v_mul_f32_e32 v86, v89, v89
	v_mul_f32_e32 v87, v91, v91
	v_fmac_f32_e32 v86, v88, v88
	v_fmac_f32_e32 v81, v80, v80
	v_mul_f32_e32 v83, v83, v83
	v_fmac_f32_e32 v87, v90, v90
	v_add_f32_e32 v80, v86, v81
	v_fmac_f32_e32 v83, v82, v82
	v_add_f32_e32 v80, v87, v80
	v_add_f32_e32 v86, v83, v80
	v_lshlrev_b32_e32 v80, 16, v76
	v_and_b32_e32 v81, 0xffff0000, v76
	v_lshlrev_b32_e32 v76, 16, v77
	v_and_b32_e32 v77, 0xffff0000, v77
	v_lshlrev_b32_e32 v82, 16, v78
	v_and_b32_e32 v83, 0xffff0000, v78
	v_lshlrev_b32_e32 v78, 16, v79
	v_and_b32_e32 v79, 0xffff0000, v79
	v_pk_add_f32 v[70:71], v[70:71], v[76:77]
	v_pk_add_f32 v[68:69], v[68:69], v[80:81]
	v_pk_add_f32 v[76:77], v[66:67], v[78:79]
	v_pk_add_f32 v[78:79], v[64:65], v[82:83]
	v_mul_f32_e32 v64, v69, v69
	v_mul_f32_e32 v65, v71, v71
	v_mul_f32_e32 v66, v79, v79
	v_fmac_f32_e32 v64, v68, v68
	v_fmac_f32_e32 v65, v70, v70
	v_mul_f32_e32 v67, v77, v77
	v_fmac_f32_e32 v66, v78, v78
	v_add_f32_e32 v64, v64, v65
	v_add_f32_e32 v64, v66, v64
	v_fmac_f32_e32 v67, v76, v76
	v_add_f32_e32 v64, v67, v64
	v_add_f32_e32 v64, v86, v64
	v_mov_b32_e32 v251, v64
	s_nop 1
	v_permlane16_swap_b32_e32 v251, v65
	s_nop 1
	v_permlane16_swap_b32_e32 v65, v251
	v_lshl_add_u64 v[80:81], s[16:17], 0, v[84:85]
	global_store_dwordx4 v[80:81], v[72:75], off
	v_cvt_pk_bf16_f32 v66, v68, v69
	v_cvt_pk_bf16_f32 v67, v70, v71
	s_waitcnt lgkmcnt(0)
	v_add_f32_e32 v64, v64, v65
	v_mov_b32_e32 v251, v64
	s_nop 1
	v_permlane32_swap_b32_e32 v251, v65
	s_nop 1
	v_permlane32_swap_b32_e32 v65, v251
	v_cvt_pk_bf16_f32 v68, v78, v79
	v_cvt_pk_bf16_f32 v69, v76, v77
	global_store_dwordx4 v[80:81], v[66:69], off offset:256
	s_and_saveexec_b64 s[34:35], s[6:7]
	s_cbranch_execz .LBB0_1431
	s_waitcnt lgkmcnt(0)
	v_add_f32_e32 v64, v64, v65
	global_atomic_add_f32 v[112:113], v64, off offset:192
.LBB0_1431:
	s_or_b64 exec, exec, s[34:35]
	v_lshl_add_u64 v[68:69], v[152:153], 1, v[144:145]
	v_lshl_add_u64 v[70:71], s[12:13], 0, v[68:69]
	s_waitcnt lgkmcnt(0)
	s_waitcnt vmcnt(15)
	v_mov_b32_e32 v64, v214
	v_mov_b32_e32 v65, v215
	v_mov_b32_e32 v66, v216
	v_mov_b32_e32 v67, v217
	v_lshlrev_b32_e32 v72, 16, v64
	v_and_b32_e32 v73, 0xffff0000, v64
	v_lshlrev_b32_e32 v64, 16, v65
	v_and_b32_e32 v65, 0xffff0000, v65
	v_lshlrev_b32_e32 v74, 16, v66
	v_and_b32_e32 v75, 0xffff0000, v66
	v_lshlrev_b32_e32 v66, 16, v67
	v_and_b32_e32 v67, 0xffff0000, v67
	v_pk_add_f32 v[64:65], v[62:63], v[64:65]
	v_pk_add_f32 v[72:73], v[60:61], v[72:73]
	v_pk_add_f32 v[66:67], v[58:59], v[66:67]
	v_pk_add_f32 v[74:75], v[56:57], v[74:75]
	v_cvt_pk_bf16_f32 v56, v72, v73
	v_cvt_pk_bf16_f32 v57, v64, v65
	v_mul_f32_e32 v65, v65, v65
	v_cvt_pk_bf16_f32 v58, v74, v75
	v_cvt_pk_bf16_f32 v59, v66, v67
	s_waitcnt vmcnt(14)
	v_mov_b32_e32 v60, v218
	v_mov_b32_e32 v61, v219
	v_mov_b32_e32 v62, v220
	v_mov_b32_e32 v63, v221
	v_mul_f32_e32 v70, v73, v73
	v_mul_f32_e32 v71, v75, v75
	v_fmac_f32_e32 v70, v72, v72
	v_fmac_f32_e32 v65, v64, v64
	v_mul_f32_e32 v67, v67, v67
	v_fmac_f32_e32 v71, v74, v74
	v_add_f32_e32 v64, v70, v65
	v_fmac_f32_e32 v67, v66, v66
	v_add_f32_e32 v64, v71, v64
	v_add_f32_e32 v70, v67, v64
	v_lshlrev_b32_e32 v64, 16, v60
	v_and_b32_e32 v65, 0xffff0000, v60
	v_lshlrev_b32_e32 v60, 16, v61
	v_and_b32_e32 v61, 0xffff0000, v61
	v_lshlrev_b32_e32 v66, 16, v62
	v_and_b32_e32 v67, 0xffff0000, v62
	v_lshlrev_b32_e32 v62, 16, v63
	v_and_b32_e32 v63, 0xffff0000, v63
	v_pk_add_f32 v[54:55], v[54:55], v[60:61]
	v_pk_add_f32 v[52:53], v[52:53], v[64:65]
	v_pk_add_f32 v[60:61], v[50:51], v[62:63]
	v_pk_add_f32 v[62:63], v[48:49], v[66:67]
	v_mul_f32_e32 v48, v53, v53
	v_mul_f32_e32 v49, v55, v55
	v_mul_f32_e32 v50, v63, v63
	v_fmac_f32_e32 v48, v52, v52
	v_fmac_f32_e32 v49, v54, v54
	v_mul_f32_e32 v51, v61, v61
	v_fmac_f32_e32 v50, v62, v62
	v_add_f32_e32 v48, v48, v49
	v_add_f32_e32 v48, v50, v48
	v_fmac_f32_e32 v51, v60, v60
	v_add_f32_e32 v48, v51, v48
	v_add_f32_e32 v48, v70, v48
	v_mov_b32_e32 v251, v48
	s_nop 1
	v_permlane16_swap_b32_e32 v251, v49
	s_nop 1
	v_permlane16_swap_b32_e32 v49, v251
	v_lshl_add_u64 v[64:65], s[16:17], 0, v[68:69]
	global_store_dwordx4 v[64:65], v[56:59], off
	v_cvt_pk_bf16_f32 v50, v52, v53
	v_cvt_pk_bf16_f32 v51, v54, v55
	s_waitcnt lgkmcnt(0)
	v_add_f32_e32 v48, v48, v49
	v_mov_b32_e32 v251, v48
	s_nop 1
	v_permlane32_swap_b32_e32 v251, v49
	s_nop 1
	v_permlane32_swap_b32_e32 v49, v251
	v_cvt_pk_bf16_f32 v52, v62, v63
	v_cvt_pk_bf16_f32 v53, v60, v61
	global_store_dwordx4 v[64:65], v[50:53], off offset:256
	s_and_saveexec_b64 s[34:35], s[6:7]
	s_cbranch_execz .LBB0_1433
	s_waitcnt lgkmcnt(0)
	v_add_f32_e32 v48, v48, v49
	global_atomic_add_f32 v[112:113], v48, off offset:512
.LBB0_1433:
	s_or_b64 exec, exec, s[34:35]
	v_lshl_add_u64 v[52:53], v[152:153], 1, v[146:147]
	v_lshl_add_u64 v[54:55], s[12:13], 0, v[52:53]
	s_waitcnt lgkmcnt(0)
	s_waitcnt vmcnt(15)
	v_mov_b32_e32 v48, v222
	v_mov_b32_e32 v49, v223
	v_mov_b32_e32 v50, v224
	v_mov_b32_e32 v51, v225
	v_lshlrev_b32_e32 v56, 16, v48
	v_and_b32_e32 v57, 0xffff0000, v48
	v_lshlrev_b32_e32 v48, 16, v49
	v_and_b32_e32 v49, 0xffff0000, v49
	v_lshlrev_b32_e32 v58, 16, v50
	v_and_b32_e32 v59, 0xffff0000, v50
	v_lshlrev_b32_e32 v50, 16, v51
	v_and_b32_e32 v51, 0xffff0000, v51
	v_pk_add_f32 v[48:49], v[46:47], v[48:49]
	v_pk_add_f32 v[56:57], v[44:45], v[56:57]
	v_pk_add_f32 v[50:51], v[42:43], v[50:51]
	v_pk_add_f32 v[58:59], v[40:41], v[58:59]
	v_cvt_pk_bf16_f32 v40, v56, v57
	v_cvt_pk_bf16_f32 v41, v48, v49
	v_mul_f32_e32 v49, v49, v49
	v_cvt_pk_bf16_f32 v42, v58, v59
	v_cvt_pk_bf16_f32 v43, v50, v51
	s_waitcnt vmcnt(14)
	v_mov_b32_e32 v44, v226
	v_mov_b32_e32 v45, v227
	v_mov_b32_e32 v46, v228
	v_mov_b32_e32 v47, v229
	v_mul_f32_e32 v54, v57, v57
	v_mul_f32_e32 v55, v59, v59
	v_fmac_f32_e32 v54, v56, v56
	v_fmac_f32_e32 v49, v48, v48
	v_mul_f32_e32 v51, v51, v51
	v_fmac_f32_e32 v55, v58, v58
	v_add_f32_e32 v48, v54, v49
	v_fmac_f32_e32 v51, v50, v50
	v_add_f32_e32 v48, v55, v48
	v_add_f32_e32 v54, v51, v48
	v_lshlrev_b32_e32 v48, 16, v44
	v_and_b32_e32 v49, 0xffff0000, v44
	v_lshlrev_b32_e32 v44, 16, v45
	v_and_b32_e32 v45, 0xffff0000, v45
	v_lshlrev_b32_e32 v50, 16, v46
	v_and_b32_e32 v51, 0xffff0000, v46
	v_lshlrev_b32_e32 v46, 16, v47
	v_and_b32_e32 v47, 0xffff0000, v47
	v_pk_add_f32 v[38:39], v[38:39], v[44:45]
	v_pk_add_f32 v[36:37], v[36:37], v[48:49]
	v_pk_add_f32 v[44:45], v[34:35], v[46:47]
	v_pk_add_f32 v[46:47], v[32:33], v[50:51]
	v_mul_f32_e32 v32, v37, v37
	v_mul_f32_e32 v33, v39, v39
	v_mul_f32_e32 v34, v47, v47
	v_fmac_f32_e32 v32, v36, v36
	v_fmac_f32_e32 v33, v38, v38
	v_mul_f32_e32 v35, v45, v45
	v_fmac_f32_e32 v34, v46, v46
	v_add_f32_e32 v32, v32, v33
	v_add_f32_e32 v32, v34, v32
	v_fmac_f32_e32 v35, v44, v44
	v_add_f32_e32 v32, v35, v32
	v_add_f32_e32 v32, v54, v32
	v_mov_b32_e32 v251, v32
	s_nop 1
	v_permlane16_swap_b32_e32 v251, v33
	s_nop 1
	v_permlane16_swap_b32_e32 v33, v251
	v_lshl_add_u64 v[48:49], s[16:17], 0, v[52:53]
	global_store_dwordx4 v[48:49], v[40:43], off
	v_cvt_pk_bf16_f32 v34, v36, v37
	v_cvt_pk_bf16_f32 v35, v38, v39
	s_waitcnt lgkmcnt(0)
	v_add_f32_e32 v32, v32, v33
	v_mov_b32_e32 v251, v32
	s_nop 1
	v_permlane32_swap_b32_e32 v251, v33
	s_nop 1
	v_permlane32_swap_b32_e32 v33, v251
	v_cvt_pk_bf16_f32 v36, v46, v47
	v_cvt_pk_bf16_f32 v37, v44, v45
	global_store_dwordx4 v[48:49], v[34:37], off offset:256
	s_and_saveexec_b64 s[34:35], s[6:7]
	s_cbranch_execz .LBB0_1435
	s_waitcnt lgkmcnt(0)
	v_add_f32_e32 v32, v32, v33
	global_atomic_add_f32 v[112:113], v32, off offset:576
.LBB0_1435:
	s_or_b64 exec, exec, s[34:35]
	v_lshl_add_u64 v[36:37], v[152:153], 1, v[148:149]
	v_lshl_add_u64 v[38:39], s[12:13], 0, v[36:37]
	s_waitcnt lgkmcnt(0)
	s_waitcnt vmcnt(15)
	v_mov_b32_e32 v32, v230
	v_mov_b32_e32 v33, v231
	v_mov_b32_e32 v34, v232
	v_mov_b32_e32 v35, v233
	v_lshlrev_b32_e32 v40, 16, v32
	v_and_b32_e32 v41, 0xffff0000, v32
	v_lshlrev_b32_e32 v32, 16, v33
	v_and_b32_e32 v33, 0xffff0000, v33
	v_lshlrev_b32_e32 v42, 16, v34
	v_and_b32_e32 v43, 0xffff0000, v34
	v_lshlrev_b32_e32 v34, 16, v35
	v_and_b32_e32 v35, 0xffff0000, v35
	v_pk_add_f32 v[32:33], v[30:31], v[32:33]
	v_pk_add_f32 v[40:41], v[28:29], v[40:41]
	v_pk_add_f32 v[34:35], v[26:27], v[34:35]
	v_pk_add_f32 v[42:43], v[24:25], v[42:43]
	v_cvt_pk_bf16_f32 v24, v40, v41
	v_cvt_pk_bf16_f32 v25, v32, v33
	v_mul_f32_e32 v33, v33, v33
	v_cvt_pk_bf16_f32 v26, v42, v43
	v_cvt_pk_bf16_f32 v27, v34, v35
	s_waitcnt vmcnt(14)
	v_mov_b32_e32 v28, v234
	v_mov_b32_e32 v29, v235
	v_mov_b32_e32 v30, v236
	v_mov_b32_e32 v31, v237
	v_mul_f32_e32 v38, v41, v41
	v_mul_f32_e32 v39, v43, v43
	v_fmac_f32_e32 v38, v40, v40
	v_fmac_f32_e32 v33, v32, v32
	v_mul_f32_e32 v35, v35, v35
	v_fmac_f32_e32 v39, v42, v42
	v_add_f32_e32 v32, v38, v33
	v_fmac_f32_e32 v35, v34, v34
	v_add_f32_e32 v32, v39, v32
	v_add_f32_e32 v38, v35, v32
	v_lshlrev_b32_e32 v32, 16, v28
	v_and_b32_e32 v33, 0xffff0000, v28
	v_lshlrev_b32_e32 v28, 16, v29
	v_and_b32_e32 v29, 0xffff0000, v29
	v_lshlrev_b32_e32 v34, 16, v30
	v_and_b32_e32 v35, 0xffff0000, v30
	v_lshlrev_b32_e32 v30, 16, v31
	v_and_b32_e32 v31, 0xffff0000, v31
	v_pk_add_f32 v[22:23], v[22:23], v[28:29]
	v_pk_add_f32 v[20:21], v[20:21], v[32:33]
	v_pk_add_f32 v[28:29], v[18:19], v[30:31]
	v_pk_add_f32 v[30:31], v[16:17], v[34:35]
	v_mul_f32_e32 v16, v21, v21
	v_mul_f32_e32 v17, v23, v23
	v_mul_f32_e32 v18, v31, v31
	v_fmac_f32_e32 v16, v20, v20
	v_fmac_f32_e32 v17, v22, v22
	v_mul_f32_e32 v19, v29, v29
	v_fmac_f32_e32 v18, v30, v30
	v_add_f32_e32 v16, v16, v17
	v_add_f32_e32 v16, v18, v16
	v_fmac_f32_e32 v19, v28, v28
	v_add_f32_e32 v16, v19, v16
	v_add_f32_e32 v16, v38, v16
	v_mov_b32_e32 v251, v16
	s_nop 1
	v_permlane16_swap_b32_e32 v251, v17
	s_nop 1
	v_permlane16_swap_b32_e32 v17, v251
	v_lshl_add_u64 v[32:33], s[16:17], 0, v[36:37]
	global_store_dwordx4 v[32:33], v[24:27], off
	v_cvt_pk_bf16_f32 v18, v20, v21
	v_cvt_pk_bf16_f32 v19, v22, v23
	s_waitcnt lgkmcnt(0)
	v_add_f32_e32 v16, v16, v17
	v_mov_b32_e32 v251, v16
	s_nop 1
	v_permlane32_swap_b32_e32 v251, v17
	s_nop 1
	v_permlane32_swap_b32_e32 v17, v251
	v_cvt_pk_bf16_f32 v20, v30, v31
	v_cvt_pk_bf16_f32 v21, v28, v29
	global_store_dwordx4 v[32:33], v[18:21], off offset:256
	s_and_saveexec_b64 s[34:35], s[6:7]
	s_cbranch_execz .LBB0_1437
	s_waitcnt lgkmcnt(0)
	v_add_f32_e32 v16, v16, v17
	global_atomic_add_f32 v[112:113], v16, off offset:640
.LBB0_1437:
	s_or_b64 exec, exec, s[34:35]
	v_lshl_add_u64 v[20:21], v[152:153], 1, v[150:151]
	v_lshl_add_u64 v[22:23], s[12:13], 0, v[20:21]
	s_waitcnt lgkmcnt(0)
	s_waitcnt vmcnt(15)
	v_mov_b32_e32 v16, v238
	v_mov_b32_e32 v17, v239
	v_mov_b32_e32 v18, v240
	v_mov_b32_e32 v19, v241
	v_lshlrev_b32_e32 v24, 16, v16
	v_and_b32_e32 v25, 0xffff0000, v16
	v_lshlrev_b32_e32 v16, 16, v17
	v_and_b32_e32 v17, 0xffff0000, v17
	v_lshlrev_b32_e32 v26, 16, v18
	v_and_b32_e32 v27, 0xffff0000, v18
	v_lshlrev_b32_e32 v18, 16, v19
	v_and_b32_e32 v19, 0xffff0000, v19
	v_pk_add_f32 v[16:17], v[14:15], v[16:17]
	v_pk_add_f32 v[24:25], v[12:13], v[24:25]
	v_pk_add_f32 v[18:19], v[10:11], v[18:19]
	v_pk_add_f32 v[26:27], v[8:9], v[26:27]
	v_cvt_pk_bf16_f32 v8, v24, v25
	v_cvt_pk_bf16_f32 v9, v16, v17
	v_mul_f32_e32 v17, v17, v17
	v_cvt_pk_bf16_f32 v10, v26, v27
	v_cvt_pk_bf16_f32 v11, v18, v19
	s_waitcnt vmcnt(14)
	v_mov_b32_e32 v12, v242
	v_mov_b32_e32 v13, v243
	v_mov_b32_e32 v14, v244
	v_mov_b32_e32 v15, v245
	v_mul_f32_e32 v22, v25, v25
	v_mul_f32_e32 v23, v27, v27
	v_fmac_f32_e32 v22, v24, v24
	v_fmac_f32_e32 v17, v16, v16
	v_mul_f32_e32 v19, v19, v19
	v_fmac_f32_e32 v23, v26, v26
	v_add_f32_e32 v16, v22, v17
	v_fmac_f32_e32 v19, v18, v18
	v_add_f32_e32 v16, v23, v16
	v_add_f32_e32 v22, v19, v16
	v_lshlrev_b32_e32 v16, 16, v12
	v_and_b32_e32 v17, 0xffff0000, v12
	v_lshlrev_b32_e32 v12, 16, v13
	v_and_b32_e32 v13, 0xffff0000, v13
	v_lshlrev_b32_e32 v18, 16, v14
	v_and_b32_e32 v19, 0xffff0000, v14
	v_lshlrev_b32_e32 v14, 16, v15
	v_and_b32_e32 v15, 0xffff0000, v15
	v_pk_add_f32 v[6:7], v[6:7], v[12:13]
	v_pk_add_f32 v[4:5], v[4:5], v[16:17]
	v_pk_add_f32 v[12:13], v[2:3], v[14:15]
	v_pk_add_f32 v[14:15], v[0:1], v[18:19]
	v_mul_f32_e32 v0, v5, v5
	v_mul_f32_e32 v1, v7, v7
	v_mul_f32_e32 v2, v15, v15
	v_fmac_f32_e32 v0, v4, v4
	v_fmac_f32_e32 v1, v6, v6
	v_mul_f32_e32 v3, v13, v13
	v_fmac_f32_e32 v2, v14, v14
	v_add_f32_e32 v0, v0, v1
	v_add_f32_e32 v0, v2, v0
	v_fmac_f32_e32 v3, v12, v12
	v_add_f32_e32 v0, v3, v0
	v_add_f32_e32 v0, v22, v0
	v_mov_b32_e32 v251, v0
	s_nop 1
	v_permlane16_swap_b32_e32 v251, v1
	s_nop 1
	v_permlane16_swap_b32_e32 v1, v251
	v_lshl_add_u64 v[16:17], s[16:17], 0, v[20:21]
	global_store_dwordx4 v[16:17], v[8:11], off
	v_cvt_pk_bf16_f32 v2, v4, v5
	v_cvt_pk_bf16_f32 v3, v6, v7
	s_waitcnt lgkmcnt(0)
	v_add_f32_e32 v0, v0, v1
	v_mov_b32_e32 v251, v0
	s_nop 1
	v_permlane32_swap_b32_e32 v251, v1
	s_nop 1
	v_permlane32_swap_b32_e32 v1, v251
	v_cvt_pk_bf16_f32 v4, v14, v15
	v_cvt_pk_bf16_f32 v5, v12, v13
	global_store_dwordx4 v[16:17], v[2:5], off offset:256
	s_and_saveexec_b64 s[34:35], s[6:7]
	s_cbranch_execz .LBB0_1439
	s_waitcnt lgkmcnt(0)
	v_add_f32_e32 v0, v0, v1
	global_atomic_add_f32 v[112:113], v0, off offset:704

.LBB0_2120:
	s_add_u32 s0, s10, 0x27000000
	s_addc_u32 s1, s11, 0
	s_add_u32 s2, s10, 0x28000
	s_addc_u32 s3, s11, 0
	s_lshl_b32 s4, s34, 8
	v_lshrrev_b32_e32 v128, 1, v192
	s_add_i32 s4, s4, s43
	v_and_b32_e32 v128, 24, v128
	v_or_b32_e32 v138, s4, v148
	v_lshl_or_b32 v128, s47, 8, v128
	v_ashrrev_i32_e32 v139, 31, v138
	v_or_b32_e32 v128, s44, v128
	v_lshlrev_b64 v[130:131], 12, v[138:139]
	v_ashrrev_i32_e32 v129, 31, v128
	v_lshl_add_u64 v[130:131], s[0:1], 0, v[130:131]
	v_lshl_add_u64 v[134:135], v[128:129], 1, v[130:131]
	global_load_dwordx4 v[172:175], v[134:135], off
	global_load_dwordx4 v[176:179], v[134:135], off offset:256
	v_add_co_u32_e32 v240, vcc, 0x10000, v134
	s_nop 1
	v_addc_co_u32_e32 v241, vcc, 0, v135, vcc
	global_load_dwordx4 v[180:183], v[240:241], off
	global_load_dwordx4 v[184:187], v[240:241], off offset:256
	v_add_co_u32_e32 v242, vcc, 0x20000, v134
	s_nop 1
	v_addc_co_u32_e32 v243, vcc, 0, v135, vcc
	global_load_dwordx4 v[188:191], v[242:243], off
	global_load_dwordx4 v[196:199], v[242:243], off offset:256
	v_add_co_u32_e32 v240, vcc, 0x30000, v134
	s_nop 1
	v_addc_co_u32_e32 v241, vcc, 0, v135, vcc
	global_load_dwordx4 v[200:203], v[240:241], off
	global_load_dwordx4 v[204:207], v[240:241], off offset:256
	v_add_co_u32_e32 v242, vcc, 0x80000, v134
	s_nop 1
	v_addc_co_u32_e32 v243, vcc, 0, v135, vcc
	global_load_dwordx4 v[208:211], v[242:243], off
	global_load_dwordx4 v[212:215], v[242:243], off offset:256
	v_add_co_u32_e32 v240, vcc, 0x90000, v134
	s_nop 1
	v_addc_co_u32_e32 v241, vcc, 0, v135, vcc
	global_load_dwordx4 v[216:219], v[240:241], off
	global_load_dwordx4 v[220:223], v[240:241], off offset:256
	v_add_co_u32_e32 v242, vcc, 0xa0000, v134
	s_nop 1
	v_addc_co_u32_e32 v243, vcc, 0, v135, vcc
	global_load_dwordx4 v[224:227], v[242:243], off
	global_load_dwordx4 v[228:231], v[242:243], off offset:256
	v_add_co_u32_e32 v240, vcc, 0xb0000, v134
	s_nop 1
	v_addc_co_u32_e32 v241, vcc, 0, v135, vcc
	global_load_dwordx4 v[232:235], v[240:241], off
	global_load_dwordx4 v[236:239], v[240:241], off offset:256
	s_waitcnt vmcnt(16)
	s_barrier
	s_waitcnt vmcnt(15)
	s_nop 0
	v_mov_b32_e32 v130, v172
	v_mov_b32_e32 v131, v173
	v_mov_b32_e32 v132, v174
	v_mov_b32_e32 v133, v175
	s_nop 0
	s_waitcnt vmcnt(14)
	s_nop 0
	v_mov_b32_e32 v134, v176
	v_mov_b32_e32 v135, v177
	v_mov_b32_e32 v136, v178
	v_mov_b32_e32 v137, v179
	v_mbcnt_lo_u32_b32 v140, -1, 0
	v_mbcnt_hi_u32_b32 v145, -1, v140
	v_and_b32_e32 v141, 64, v145
	v_xor_b32_e32 v140, 16, v145
	v_add_u32_e32 v152, 64, v141
	v_cmp_lt_i32_e32 vcc, v140, v152
	v_and_b32_e32 v141, 0xffff0000, v130
	v_cndmask_b32_e32 v140, v145, v140, vcc
	v_lshlrev_b32_e32 v144, 2, v140
	v_lshlrev_b32_e32 v140, 16, v130
	v_lshlrev_b32_e32 v130, 16, v131
	v_and_b32_e32 v131, 0xffff0000, v131
	v_lshlrev_b32_e32 v148, 16, v134
	v_and_b32_e32 v149, 0xffff0000, v134
	v_lshlrev_b32_e32 v134, 16, v135
	v_and_b32_e32 v135, 0xffff0000, v135
	v_lshlrev_b32_e32 v142, 16, v132
	v_and_b32_e32 v143, 0xffff0000, v132
	v_lshlrev_b32_e32 v146, 16, v133
	v_and_b32_e32 v147, 0xffff0000, v133
	v_lshlrev_b32_e32 v150, 16, v136
	v_and_b32_e32 v151, 0xffff0000, v136
	v_pk_add_f32 v[126:127], v[126:127], v[130:131]
	v_pk_add_f32 v[132:133], v[124:125], v[140:141]
	v_pk_add_f32 v[118:119], v[118:119], v[134:135]
	v_pk_add_f32 v[116:117], v[116:117], v[148:149]
	v_lshlrev_b32_e32 v136, 16, v137
	v_and_b32_e32 v137, 0xffff0000, v137
	v_pk_add_f32 v[124:125], v[120:121], v[142:143]
	v_pk_add_f32 v[120:121], v[112:113], v[150:151]
	v_mul_f32_e32 v112, v133, v133
	v_mul_f32_e32 v113, v127, v127
	v_mul_f32_e32 v134, v117, v117
	v_mul_f32_e32 v135, v119, v119
	v_pk_add_f32 v[122:123], v[122:123], v[146:147]
	v_pk_add_f32 v[114:115], v[114:115], v[136:137]
	v_mul_f32_e32 v130, v125, v125
	v_mul_f32_e32 v136, v121, v121
	v_fmac_f32_e32 v112, v132, v132
	v_fmac_f32_e32 v113, v126, v126
	v_fmac_f32_e32 v134, v116, v116
	v_fmac_f32_e32 v135, v118, v118
	v_mul_f32_e32 v131, v123, v123
	v_mul_f32_e32 v137, v115, v115
	v_fmac_f32_e32 v130, v124, v124
	v_fmac_f32_e32 v136, v120, v120
	v_add_f32_e32 v112, v112, v113
	v_add_f32_e32 v113, v134, v135
	v_fmac_f32_e32 v131, v122, v122
	v_fmac_f32_e32 v137, v114, v114
	v_add_f32_e32 v112, v130, v112
	v_add_f32_e32 v113, v136, v113
	v_add_f32_e32 v112, v131, v112
	v_add_f32_e32 v113, v137, v113
	v_add_f32_e32 v112, v112, v113
	v_mov_b32_e32 v251, v112
	s_nop 1
	v_permlane16_swap_b32_e32 v251, v113
	s_nop 1
	v_permlane16_swap_b32_e32 v113, v251
	v_xor_b32_e32 v130, 32, v145
	v_cmp_lt_i32_e32 vcc, v130, v152
	s_nop 1
	v_cndmask_b32_e32 v130, v145, v130, vcc
	v_lshlrev_b32_e32 v146, 2, v130
	s_waitcnt lgkmcnt(0)
	v_add_f32_e32 v130, v112, v113
	v_mov_b32_e32 v251, v130
	s_nop 1
	v_permlane32_swap_b32_e32 v251, v131
	s_nop 1
	v_permlane32_swap_b32_e32 v131, v251
	v_and_b32_e32 v145, 63, v192
	v_cmp_gt_u32_e32 vcc, 16, v145
	v_lshl_add_u64 v[112:113], v[138:139], 2, s[2:3]
	s_and_saveexec_b64 s[4:5], vcc
	s_cbranch_execz .LBB0_2122
	s_waitcnt lgkmcnt(0)
	v_add_f32_e32 v130, v130, v131
	global_atomic_add_f32 v[112:113], v130, off
.LBB0_2122:
	s_or_b64 exec, exec, s[4:5]
	v_or_b32_e32 v136, 16, v138
	v_ashrrev_i32_e32 v137, 31, v136
	s_waitcnt lgkmcnt(0)
	v_lshlrev_b64 v[130:131], 12, v[136:137]
	v_lshl_add_u64 v[130:131], s[0:1], 0, v[130:131]
	v_lshl_add_u64 v[130:131], v[128:129], 1, v[130:131]
	s_waitcnt vmcnt(13)
	s_nop 0
	v_mov_b32_e32 v140, v180
	v_mov_b32_e32 v141, v181
	v_mov_b32_e32 v142, v182
	v_mov_b32_e32 v143, v183
	s_waitcnt vmcnt(12)
	s_nop 0
	v_mov_b32_e32 v148, v184
	v_mov_b32_e32 v149, v185
	v_mov_b32_e32 v150, v186
	v_mov_b32_e32 v151, v187
	v_lshlrev_b32_e32 v130, 16, v140
	v_and_b32_e32 v131, 0xffff0000, v140
	v_lshlrev_b32_e32 v134, 16, v141
	v_and_b32_e32 v135, 0xffff0000, v141
	v_lshlrev_b32_e32 v152, 16, v148
	v_and_b32_e32 v153, 0xffff0000, v148
	v_lshlrev_b32_e32 v148, 16, v149
	v_and_b32_e32 v149, 0xffff0000, v149
	v_lshlrev_b32_e32 v140, 16, v142
	v_and_b32_e32 v141, 0xffff0000, v142
	v_lshlrev_b32_e32 v154, 16, v150
	v_and_b32_e32 v155, 0xffff0000, v150
	v_pk_add_f32 v[110:111], v[110:111], v[134:135]
	v_pk_add_f32 v[130:131], v[108:109], v[130:131]
	v_pk_add_f32 v[102:103], v[102:103], v[148:149]
	v_pk_add_f32 v[100:101], v[100:101], v[152:153]
	v_lshlrev_b32_e32 v142, 16, v143
	v_and_b32_e32 v143, 0xffff0000, v143
	v_lshlrev_b32_e32 v150, 16, v151
	v_and_b32_e32 v151, 0xffff0000, v151
	v_pk_add_f32 v[104:105], v[104:105], v[140:141]
	v_pk_add_f32 v[96:97], v[96:97], v[154:155]
	v_mul_f32_e32 v108, v131, v131
	v_mul_f32_e32 v109, v111, v111
	v_mul_f32_e32 v140, v101, v101
	v_mul_f32_e32 v141, v103, v103
	v_pk_add_f32 v[106:107], v[106:107], v[142:143]
	v_pk_add_f32 v[98:99], v[98:99], v[150:151]
	v_mul_f32_e32 v134, v105, v105
	v_mul_f32_e32 v142, v97, v97
	v_fmac_f32_e32 v108, v130, v130
	v_fmac_f32_e32 v109, v110, v110
	v_fmac_f32_e32 v140, v100, v100
	v_fmac_f32_e32 v141, v102, v102
	v_mul_f32_e32 v135, v107, v107
	v_mul_f32_e32 v143, v99, v99
	v_fmac_f32_e32 v134, v104, v104
	v_fmac_f32_e32 v142, v96, v96
	v_add_f32_e32 v108, v108, v109
	v_add_f32_e32 v109, v140, v141
	v_fmac_f32_e32 v135, v106, v106
	v_fmac_f32_e32 v143, v98, v98
	v_add_f32_e32 v108, v134, v108
	v_add_f32_e32 v109, v142, v109
	v_add_f32_e32 v108, v135, v108
	v_add_f32_e32 v109, v143, v109
	v_add_f32_e32 v108, v108, v109
	v_mov_b32_e32 v251, v108
	s_nop 1
	v_permlane16_swap_b32_e32 v251, v109
	s_nop 1
	v_permlane16_swap_b32_e32 v109, v251
	s_waitcnt lgkmcnt(0)
	v_add_f32_e32 v108, v108, v109
	v_mov_b32_e32 v251, v108
	s_nop 1
	v_permlane32_swap_b32_e32 v251, v109
	s_nop 1
	v_permlane32_swap_b32_e32 v109, v251
	s_and_saveexec_b64 s[4:5], vcc
	s_cbranch_execz .LBB0_2124
	s_waitcnt lgkmcnt(0)
	v_add_f32_e32 v108, v108, v109
	global_atomic_add_f32 v[112:113], v108, off offset:64
.LBB0_2124:
	s_or_b64 exec, exec, s[4:5]
	v_or_b32_e32 v134, 32, v138
	v_ashrrev_i32_e32 v135, 31, v134
	s_waitcnt lgkmcnt(0)
	v_lshlrev_b64 v[108:109], 12, v[134:135]
	v_lshl_add_u64 v[108:109], s[0:1], 0, v[108:109]
	v_lshl_add_u64 v[108:109], v[128:129], 1, v[108:109]
	s_waitcnt vmcnt(11)
	s_nop 0
	v_mov_b32_e32 v140, v188
	v_mov_b32_e32 v141, v189
	v_mov_b32_e32 v142, v190
	v_mov_b32_e32 v143, v191
	s_waitcnt vmcnt(10)
	s_nop 0
	v_mov_b32_e32 v148, v196
	v_mov_b32_e32 v149, v197
	v_mov_b32_e32 v150, v198
	v_mov_b32_e32 v151, v199
	v_lshlrev_b32_e32 v108, 16, v140
	v_and_b32_e32 v109, 0xffff0000, v140
	v_lshlrev_b32_e32 v140, 16, v141
	v_and_b32_e32 v141, 0xffff0000, v141
	v_lshlrev_b32_e32 v154, 16, v148
	v_and_b32_e32 v155, 0xffff0000, v148
	v_lshlrev_b32_e32 v148, 16, v149
	v_and_b32_e32 v149, 0xffff0000, v149
	v_lshlrev_b32_e32 v152, 16, v142
	v_and_b32_e32 v153, 0xffff0000, v142
	v_lshlrev_b32_e32 v142, 16, v143
	v_and_b32_e32 v143, 0xffff0000, v143
	v_lshlrev_b32_e32 v156, 16, v150
	v_and_b32_e32 v157, 0xffff0000, v150
	v_pk_add_f32 v[94:95], v[94:95], v[140:141]
	v_pk_add_f32 v[92:93], v[92:93], v[108:109]
	v_pk_add_f32 v[86:87], v[86:87], v[148:149]
	v_pk_add_f32 v[84:85], v[84:85], v[154:155]
	v_lshlrev_b32_e32 v150, 16, v151
	v_and_b32_e32 v151, 0xffff0000, v151
	v_pk_add_f32 v[90:91], v[90:91], v[142:143]
	v_pk_add_f32 v[88:89], v[88:89], v[152:153]
	v_pk_add_f32 v[80:81], v[80:81], v[156:157]
	v_mul_f32_e32 v108, v93, v93
	v_mul_f32_e32 v109, v95, v95
	v_mul_f32_e32 v142, v85, v85
	v_mul_f32_e32 v143, v87, v87
	v_pk_add_f32 v[82:83], v[82:83], v[150:151]
	v_mul_f32_e32 v140, v89, v89
	v_mul_f32_e32 v147, v81, v81
	v_fmac_f32_e32 v108, v92, v92
	v_fmac_f32_e32 v109, v94, v94
	v_fmac_f32_e32 v142, v84, v84
	v_fmac_f32_e32 v143, v86, v86
	v_mul_f32_e32 v141, v91, v91
	v_mul_f32_e32 v148, v83, v83
	v_fmac_f32_e32 v140, v88, v88
	v_fmac_f32_e32 v147, v80, v80
	v_add_f32_e32 v108, v108, v109
	v_add_f32_e32 v109, v142, v143
	v_fmac_f32_e32 v141, v90, v90
	v_fmac_f32_e32 v148, v82, v82
	v_add_f32_e32 v108, v140, v108
	v_add_f32_e32 v109, v147, v109
	v_add_f32_e32 v108, v141, v108
	v_add_f32_e32 v109, v148, v109
	v_add_f32_e32 v108, v108, v109
	v_mov_b32_e32 v251, v108
	s_nop 1
	v_permlane16_swap_b32_e32 v251, v109
	s_nop 1
	v_permlane16_swap_b32_e32 v109, v251
	s_waitcnt lgkmcnt(0)
	v_add_f32_e32 v108, v108, v109
	v_mov_b32_e32 v251, v108
	s_nop 1
	v_permlane32_swap_b32_e32 v251, v109
	s_nop 1
	v_permlane32_swap_b32_e32 v109, v251
	s_and_saveexec_b64 s[4:5], vcc
	s_cbranch_execz .LBB0_2126
	s_waitcnt lgkmcnt(0)
	v_add_f32_e32 v108, v108, v109
	global_atomic_add_f32 v[112:113], v108, off offset:128
.LBB0_2126:
	s_or_b64 exec, exec, s[4:5]
	v_or_b32_e32 v108, 48, v138
	s_waitcnt lgkmcnt(0)
	v_ashrrev_i32_e32 v109, 31, v108
	v_lshlrev_b64 v[140:141], 12, v[108:109]
	v_lshl_add_u64 v[140:141], s[0:1], 0, v[140:141]
	v_lshl_add_u64 v[148:149], v[128:129], 1, v[140:141]
	s_waitcnt vmcnt(9)
	s_nop 0
	v_mov_b32_e32 v140, v200
	v_mov_b32_e32 v141, v201
	v_mov_b32_e32 v142, v202
	v_mov_b32_e32 v143, v203
	s_nop 0
	s_waitcnt vmcnt(8)
	s_nop 0
	v_mov_b32_e32 v148, v204
	v_mov_b32_e32 v149, v205
	v_mov_b32_e32 v150, v206
	v_mov_b32_e32 v151, v207
	v_lshlrev_b32_e32 v152, 16, v140
	v_and_b32_e32 v153, 0xffff0000, v140
	v_lshlrev_b32_e32 v140, 16, v141
	v_and_b32_e32 v141, 0xffff0000, v141
	v_lshlrev_b32_e32 v156, 16, v148
	v_and_b32_e32 v157, 0xffff0000, v148
	v_lshlrev_b32_e32 v148, 16, v149
	v_and_b32_e32 v149, 0xffff0000, v149
	v_lshlrev_b32_e32 v154, 16, v142
	v_and_b32_e32 v155, 0xffff0000, v142
	v_lshlrev_b32_e32 v158, 16, v150
	v_and_b32_e32 v159, 0xffff0000, v150
	v_pk_add_f32 v[78:79], v[78:79], v[140:141]
	v_pk_add_f32 v[76:77], v[76:77], v[152:153]
	v_pk_add_f32 v[70:71], v[70:71], v[148:149]
	v_pk_add_f32 v[68:69], v[68:69], v[156:157]
	v_lshlrev_b32_e32 v142, 16, v143
	v_and_b32_e32 v143, 0xffff0000, v143
	v_lshlrev_b32_e32 v150, 16, v151
	v_and_b32_e32 v151, 0xffff0000, v151
	v_pk_add_f32 v[72:73], v[72:73], v[154:155]
	v_pk_add_f32 v[64:65], v[64:65], v[158:159]
	v_mul_f32_e32 v140, v77, v77
	v_mul_f32_e32 v141, v79, v79
	v_mul_f32_e32 v147, v69, v69
	v_mul_f32_e32 v148, v71, v71
	v_pk_add_f32 v[74:75], v[74:75], v[142:143]
	v_pk_add_f32 v[66:67], v[66:67], v[150:151]
	v_mul_f32_e32 v142, v73, v73
	v_mul_f32_e32 v149, v65, v65
	v_fmac_f32_e32 v140, v76, v76
	v_fmac_f32_e32 v141, v78, v78
	v_fmac_f32_e32 v147, v68, v68
	v_fmac_f32_e32 v148, v70, v70
	v_mul_f32_e32 v143, v75, v75
	v_mul_f32_e32 v150, v67, v67
	v_fmac_f32_e32 v142, v72, v72
	v_fmac_f32_e32 v149, v64, v64
	v_add_f32_e32 v140, v140, v141
	v_add_f32_e32 v141, v147, v148
	v_fmac_f32_e32 v143, v74, v74
	v_fmac_f32_e32 v150, v66, v66
	v_add_f32_e32 v140, v142, v140
	v_add_f32_e32 v141, v149, v141
	v_add_f32_e32 v140, v143, v140
	v_add_f32_e32 v141, v150, v141
	v_add_f32_e32 v140, v140, v141
	v_mov_b32_e32 v251, v140
	s_nop 1
	v_permlane16_swap_b32_e32 v251, v141
	s_nop 1
	v_permlane16_swap_b32_e32 v141, v251
	s_waitcnt lgkmcnt(0)
	v_add_f32_e32 v140, v140, v141
	v_mov_b32_e32 v251, v140
	s_nop 1
	v_permlane32_swap_b32_e32 v251, v141
	s_nop 1
	v_permlane32_swap_b32_e32 v141, v251
	s_and_saveexec_b64 s[4:5], vcc
	s_cbranch_execz .LBB0_2128
	s_waitcnt lgkmcnt(0)
	v_add_f32_e32 v140, v140, v141
	global_atomic_add_f32 v[112:113], v140, off offset:192
.LBB0_2128:
	s_or_b64 exec, exec, s[4:5]
	v_add_u32_e32 v140, 0x80, v138
	s_waitcnt lgkmcnt(0)
	v_ashrrev_i32_e32 v141, 31, v140
	v_lshlrev_b64 v[142:143], 12, v[140:141]
	v_lshl_add_u64 v[142:143], s[0:1], 0, v[142:143]
	v_lshl_add_u64 v[142:143], v[128:129], 1, v[142:143]
	s_waitcnt vmcnt(7)
	s_nop 0
	v_mov_b32_e32 v148, v208
	v_mov_b32_e32 v149, v209
	v_mov_b32_e32 v150, v210
	v_mov_b32_e32 v151, v211
	s_waitcnt vmcnt(6)
	s_nop 0
	v_mov_b32_e32 v152, v212
	v_mov_b32_e32 v153, v213
	v_mov_b32_e32 v154, v214
	v_mov_b32_e32 v155, v215
	v_lshlrev_b32_e32 v142, 16, v148
	v_and_b32_e32 v143, 0xffff0000, v148
	v_lshlrev_b32_e32 v148, 16, v149
	v_and_b32_e32 v149, 0xffff0000, v149
	v_lshlrev_b32_e32 v158, 16, v152
	v_and_b32_e32 v159, 0xffff0000, v152
	v_lshlrev_b32_e32 v152, 16, v153
	v_and_b32_e32 v153, 0xffff0000, v153
	v_lshlrev_b32_e32 v156, 16, v150
	v_and_b32_e32 v157, 0xffff0000, v150
	v_lshlrev_b32_e32 v150, 16, v151
	v_and_b32_e32 v151, 0xffff0000, v151
	v_lshlrev_b32_e32 v160, 16, v154
	v_and_b32_e32 v161, 0xffff0000, v154
	v_pk_add_f32 v[62:63], v[62:63], v[148:149]
	v_pk_add_f32 v[60:61], v[60:61], v[142:143]
	v_pk_add_f32 v[54:55], v[54:55], v[152:153]
	v_pk_add_f32 v[52:53], v[52:53], v[158:159]
	v_lshlrev_b32_e32 v154, 16, v155
	v_and_b32_e32 v155, 0xffff0000, v155
	v_pk_add_f32 v[58:59], v[58:59], v[150:151]
	v_pk_add_f32 v[56:57], v[56:57], v[156:157]
	v_pk_add_f32 v[48:49], v[48:49], v[160:161]
	v_mul_f32_e32 v142, v61, v61
	v_mul_f32_e32 v143, v63, v63
	v_mul_f32_e32 v149, v53, v53
	v_mul_f32_e32 v150, v55, v55
	v_pk_add_f32 v[50:51], v[50:51], v[154:155]
	v_mul_f32_e32 v147, v57, v57
	v_mul_f32_e32 v151, v49, v49
	v_fmac_f32_e32 v142, v60, v60
	v_fmac_f32_e32 v143, v62, v62
	v_fmac_f32_e32 v149, v52, v52
	v_fmac_f32_e32 v150, v54, v54
	v_mul_f32_e32 v148, v59, v59
	v_mul_f32_e32 v152, v51, v51
	v_fmac_f32_e32 v147, v56, v56
	v_fmac_f32_e32 v151, v48, v48
	v_add_f32_e32 v142, v142, v143
	v_add_f32_e32 v143, v149, v150
	v_fmac_f32_e32 v148, v58, v58
	v_fmac_f32_e32 v152, v50, v50
	v_add_f32_e32 v142, v147, v142
	v_add_f32_e32 v143, v151, v143
	v_add_f32_e32 v142, v148, v142
	v_add_f32_e32 v143, v152, v143
	v_add_f32_e32 v142, v142, v143
	v_mov_b32_e32 v251, v142
	s_nop 1
	v_permlane16_swap_b32_e32 v251, v143
	s_nop 1
	v_permlane16_swap_b32_e32 v143, v251
	s_waitcnt lgkmcnt(0)
	v_add_f32_e32 v142, v142, v143
	v_mov_b32_e32 v251, v142
	s_nop 1
	v_permlane32_swap_b32_e32 v251, v143
	s_nop 1
	v_permlane32_swap_b32_e32 v143, v251
	s_and_saveexec_b64 s[4:5], vcc
	s_cbranch_execz .LBB0_2130
	s_waitcnt lgkmcnt(0)
	v_add_f32_e32 v142, v142, v143
	global_atomic_add_f32 v[112:113], v142, off offset:512
.LBB0_2130:
	s_or_b64 exec, exec, s[4:5]
	v_add_u32_e32 v142, 0x90, v138
	s_waitcnt lgkmcnt(0)
	v_ashrrev_i32_e32 v143, 31, v142
	v_lshlrev_b64 v[148:149], 12, v[142:143]
	v_lshl_add_u64 v[148:149], s[0:1], 0, v[148:149]
	v_lshl_add_u64 v[152:153], v[128:129], 1, v[148:149]
	s_waitcnt vmcnt(5)
	s_nop 0
	v_mov_b32_e32 v148, v216
	v_mov_b32_e32 v149, v217
	v_mov_b32_e32 v150, v218
	v_mov_b32_e32 v151, v219
	s_nop 0
	s_waitcnt vmcnt(4)
	s_nop 0
	v_mov_b32_e32 v152, v220
	v_mov_b32_e32 v153, v221
	v_mov_b32_e32 v154, v222
	v_mov_b32_e32 v155, v223
	v_lshlrev_b32_e32 v156, 16, v148
	v_and_b32_e32 v157, 0xffff0000, v148
	v_lshlrev_b32_e32 v148, 16, v149
	v_and_b32_e32 v149, 0xffff0000, v149
	v_lshlrev_b32_e32 v160, 16, v152
	v_and_b32_e32 v161, 0xffff0000, v152
	v_lshlrev_b32_e32 v152, 16, v153
	v_and_b32_e32 v153, 0xffff0000, v153
	v_lshlrev_b32_e32 v158, 16, v150
	v_and_b32_e32 v159, 0xffff0000, v150
	v_lshlrev_b32_e32 v150, 16, v151
	v_and_b32_e32 v151, 0xffff0000, v151
	v_lshlrev_b32_e32 v162, 16, v154
	v_and_b32_e32 v163, 0xffff0000, v154
	v_pk_add_f32 v[46:47], v[46:47], v[148:149]
	v_pk_add_f32 v[44:45], v[44:45], v[156:157]
	v_pk_add_f32 v[38:39], v[38:39], v[152:153]
	v_pk_add_f32 v[36:37], v[36:37], v[160:161]
	v_lshlrev_b32_e32 v154, 16, v155
	v_and_b32_e32 v155, 0xffff0000, v155
	v_pk_add_f32 v[42:43], v[42:43], v[150:151]
	v_pk_add_f32 v[40:41], v[40:41], v[158:159]
	v_pk_add_f32 v[32:33], v[32:33], v[162:163]
	v_mul_f32_e32 v147, v45, v45
	v_mul_f32_e32 v148, v47, v47
	v_mul_f32_e32 v151, v37, v37
	v_mul_f32_e32 v152, v39, v39
	v_pk_add_f32 v[34:35], v[34:35], v[154:155]
	v_mul_f32_e32 v149, v41, v41
	v_mul_f32_e32 v153, v33, v33
	v_fmac_f32_e32 v147, v44, v44
	v_fmac_f32_e32 v148, v46, v46
	v_fmac_f32_e32 v151, v36, v36
	v_fmac_f32_e32 v152, v38, v38
	v_mul_f32_e32 v150, v43, v43
	v_mul_f32_e32 v154, v35, v35
	v_fmac_f32_e32 v149, v40, v40
	v_fmac_f32_e32 v153, v32, v32
	v_add_f32_e32 v147, v147, v148
	v_add_f32_e32 v148, v151, v152
	v_fmac_f32_e32 v150, v42, v42
	v_fmac_f32_e32 v154, v34, v34
	v_add_f32_e32 v147, v149, v147
	v_add_f32_e32 v148, v153, v148
	v_add_f32_e32 v147, v150, v147
	v_add_f32_e32 v148, v154, v148
	v_add_f32_e32 v147, v147, v148
	v_mov_b32_e32 v251, v147
	s_nop 1
	v_permlane16_swap_b32_e32 v251, v148
	s_nop 1
	v_permlane16_swap_b32_e32 v148, v251
	s_waitcnt lgkmcnt(0)
	v_add_f32_e32 v147, v147, v148
	v_mov_b32_e32 v251, v147
	s_nop 1
	v_permlane32_swap_b32_e32 v251, v148
	s_nop 1
	v_permlane32_swap_b32_e32 v148, v251
	s_and_saveexec_b64 s[4:5], vcc
	s_cbranch_execz .LBB0_2132
	s_waitcnt lgkmcnt(0)
	v_add_f32_e32 v147, v147, v148
	global_atomic_add_f32 v[112:113], v147, off offset:576
.LBB0_2132:
	s_or_b64 exec, exec, s[4:5]
	v_add_u32_e32 v152, 0xa0, v138
	v_ashrrev_i32_e32 v153, 31, v152
	s_waitcnt lgkmcnt(0)
	v_lshlrev_b64 v[148:149], 12, v[152:153]
	v_lshl_add_u64 v[148:149], s[0:1], 0, v[148:149]
	v_lshl_add_u64 v[154:155], v[128:129], 1, v[148:149]
	s_waitcnt vmcnt(3)
	s_nop 0
	v_mov_b32_e32 v148, v224
	v_mov_b32_e32 v149, v225
	v_mov_b32_e32 v150, v226
	v_mov_b32_e32 v151, v227
	s_nop 0
	s_waitcnt vmcnt(2)
	s_nop 0
	v_mov_b32_e32 v154, v228
	v_mov_b32_e32 v155, v229
	v_mov_b32_e32 v156, v230
	v_mov_b32_e32 v157, v231
	v_lshlrev_b32_e32 v158, 16, v148
	v_and_b32_e32 v159, 0xffff0000, v148
	v_lshlrev_b32_e32 v148, 16, v149
	v_and_b32_e32 v149, 0xffff0000, v149
	v_lshlrev_b32_e32 v162, 16, v154
	v_and_b32_e32 v163, 0xffff0000, v154
	v_lshlrev_b32_e32 v154, 16, v155
	v_and_b32_e32 v155, 0xffff0000, v155
	v_lshlrev_b32_e32 v160, 16, v150
	v_and_b32_e32 v161, 0xffff0000, v150
	v_lshlrev_b32_e32 v150, 16, v151
	v_and_b32_e32 v151, 0xffff0000, v151
	v_lshlrev_b32_e32 v164, 16, v156
	v_and_b32_e32 v165, 0xffff0000, v156
	v_pk_add_f32 v[30:31], v[30:31], v[148:149]
	v_pk_add_f32 v[28:29], v[28:29], v[158:159]
	v_pk_add_f32 v[22:23], v[22:23], v[154:155]
	v_pk_add_f32 v[20:21], v[20:21], v[162:163]
	v_lshlrev_b32_e32 v156, 16, v157
	v_and_b32_e32 v157, 0xffff0000, v157
	v_pk_add_f32 v[26:27], v[26:27], v[150:151]
	v_pk_add_f32 v[24:25], v[24:25], v[160:161]
	v_pk_add_f32 v[16:17], v[16:17], v[164:165]
	v_mul_f32_e32 v147, v29, v29
	v_mul_f32_e32 v148, v31, v31
	v_mul_f32_e32 v151, v21, v21
	v_mul_f32_e32 v154, v23, v23
	v_pk_add_f32 v[18:19], v[18:19], v[156:157]
	v_mul_f32_e32 v149, v25, v25
	v_mul_f32_e32 v155, v17, v17
	v_fmac_f32_e32 v147, v28, v28
	v_fmac_f32_e32 v148, v30, v30
	v_fmac_f32_e32 v151, v20, v20
	v_fmac_f32_e32 v154, v22, v22
	v_mul_f32_e32 v150, v27, v27
	v_mul_f32_e32 v156, v19, v19
	v_fmac_f32_e32 v149, v24, v24
	v_fmac_f32_e32 v155, v16, v16
	v_add_f32_e32 v147, v147, v148
	v_add_f32_e32 v148, v151, v154
	v_fmac_f32_e32 v150, v26, v26
	v_fmac_f32_e32 v156, v18, v18
	v_add_f32_e32 v147, v149, v147
	v_add_f32_e32 v148, v155, v148
	v_add_f32_e32 v147, v150, v147
	v_add_f32_e32 v148, v156, v148
	v_add_f32_e32 v147, v147, v148
	v_mov_b32_e32 v251, v147
	s_nop 1
	v_permlane16_swap_b32_e32 v251, v148
	s_nop 1
	v_permlane16_swap_b32_e32 v148, v251
	s_waitcnt lgkmcnt(0)
	v_add_f32_e32 v147, v147, v148
	v_mov_b32_e32 v251, v147
	s_nop 1
	v_permlane32_swap_b32_e32 v251, v148
	s_nop 1
	v_permlane32_swap_b32_e32 v148, v251
	s_and_saveexec_b64 s[4:5], vcc
	s_cbranch_execz .LBB0_2134
	s_waitcnt lgkmcnt(0)
	v_add_f32_e32 v147, v147, v148
	global_atomic_add_f32 v[112:113], v147, off offset:640
.LBB0_2134:
	s_or_b64 exec, exec, s[4:5]
	v_add_u32_e32 v156, 0xb0, v138
	v_ashrrev_i32_e32 v157, 31, v156
	s_waitcnt lgkmcnt(0)
	v_lshlrev_b64 v[148:149], 12, v[156:157]
	v_lshl_add_u64 v[148:149], s[0:1], 0, v[148:149]
	v_lshl_add_u64 v[154:155], v[128:129], 1, v[148:149]
	s_waitcnt vmcnt(1)
	s_nop 0
	v_mov_b32_e32 v148, v232
	v_mov_b32_e32 v149, v233
	v_mov_b32_e32 v150, v234
	v_mov_b32_e32 v151, v235
	s_waitcnt vmcnt(0)
	s_nop 0
	v_mov_b32_e32 v158, v236
	v_mov_b32_e32 v159, v237
	v_mov_b32_e32 v160, v238
	v_mov_b32_e32 v161, v239
	v_lshlrev_b32_e32 v154, 16, v148
	v_and_b32_e32 v155, 0xffff0000, v148
	v_lshlrev_b32_e32 v148, 16, v149
	v_and_b32_e32 v149, 0xffff0000, v149
	v_lshlrev_b32_e32 v164, 16, v158
	v_and_b32_e32 v165, 0xffff0000, v158
	v_lshlrev_b32_e32 v158, 16, v159
	v_and_b32_e32 v159, 0xffff0000, v159
	v_lshlrev_b32_e32 v162, 16, v150
	v_and_b32_e32 v163, 0xffff0000, v150
	v_lshlrev_b32_e32 v150, 16, v151
	v_and_b32_e32 v151, 0xffff0000, v151
	v_lshlrev_b32_e32 v166, 16, v160
	v_and_b32_e32 v167, 0xffff0000, v160
	v_pk_add_f32 v[14:15], v[14:15], v[148:149]
	v_pk_add_f32 v[12:13], v[12:13], v[154:155]
	v_pk_add_f32 v[6:7], v[6:7], v[158:159]
	v_pk_add_f32 v[4:5], v[4:5], v[164:165]
	v_lshlrev_b32_e32 v160, 16, v161
	v_and_b32_e32 v161, 0xffff0000, v161
	v_pk_add_f32 v[10:11], v[10:11], v[150:151]
	v_pk_add_f32 v[8:9], v[8:9], v[162:163]
	v_pk_add_f32 v[0:1], v[0:1], v[166:167]
	v_mul_f32_e32 v147, v13, v13
	v_mul_f32_e32 v148, v15, v15
	v_mul_f32_e32 v151, v5, v5
	v_mul_f32_e32 v154, v7, v7
	v_pk_add_f32 v[2:3], v[2:3], v[160:161]
	v_mul_f32_e32 v149, v9, v9
	v_mul_f32_e32 v155, v1, v1
	v_fmac_f32_e32 v147, v12, v12
	v_fmac_f32_e32 v148, v14, v14
	v_fmac_f32_e32 v151, v4, v4
	v_fmac_f32_e32 v154, v6, v6
	v_mul_f32_e32 v150, v11, v11
	v_mul_f32_e32 v158, v3, v3
	v_fmac_f32_e32 v149, v8, v8
	v_fmac_f32_e32 v155, v0, v0
	v_add_f32_e32 v147, v147, v148
	v_add_f32_e32 v148, v151, v154
	v_fmac_f32_e32 v150, v10, v10
	v_fmac_f32_e32 v158, v2, v2
	v_add_f32_e32 v147, v149, v147
	v_add_f32_e32 v148, v155, v148
	v_add_f32_e32 v147, v150, v147
	v_add_f32_e32 v148, v158, v148
	v_add_f32_e32 v147, v147, v148
	v_mov_b32_e32 v251, v147
	s_nop 1
	v_permlane16_swap_b32_e32 v251, v144
	s_nop 1
	v_permlane16_swap_b32_e32 v144, v251
	s_waitcnt lgkmcnt(0)
	v_add_f32_e32 v144, v147, v144
	v_mov_b32_e32 v251, v144
	s_nop 1
	v_permlane32_swap_b32_e32 v251, v146
	s_nop 1
	v_permlane32_swap_b32_e32 v146, v251
	s_and_saveexec_b64 s[0:1], vcc
	s_cbranch_execz .LBB0_2136
	s_waitcnt lgkmcnt(0)
	v_add_f32_e32 v144, v144, v146
	global_atomic_add_f32 v[112:113], v144, off offset:704
